# pool: in-loop weight batches issued one batch ahead (as fourier_out); plus earlier gmlp LDS read pipelining
# speedup vs baseline: 1.0007x; 1.0007x over previous
.LBB0_235:
	global_load_dwordx4 v[90:93], v[74:75], off
	global_load_dwordx4 v[94:97], v[72:73], off
	global_load_dwordx4 v[106:109], v[72:73], off offset:2048
	global_load_dwordx4 v[110:113], v[76:77], off
	v_add_u32_e32 v56, s9, v137
	v_mov_b32_e32 v131, v209
	s_ashr_i32 s11, s9, 31
	s_lshr_b32 s11, s11, 19
	s_add_i32 s11, s9, s11
	s_and_b32 s11, s11, 0xffffe000
	s_sub_i32 s11, s9, s11
	s_add_i32 s18, s11, -8
	s_add_i32 s0, s0, s3
	s_add_u32 s100, s84, s58
	s_addc_u32 s101, s85, 0
	v_add_u32_e32 v0, 0, v56
	v_max_i32_e32 v0, 8, v0
	v_add_u32_e32 v0, -8, v0
	v_min_u32_e32 v0, 0xffff, v0
	v_mul_u32_u24_e32 v208, 0xe00, v0
	v_lshl_add_u64 v[0:1], s[100:101], 0, v[208:209]
	v_lshl_add_u64 v[0:1], v[0:1], 0, v[130:131]
	global_load_dwordx4 v[0:3], v[0:1], off offset:1536
	v_add_u32_e32 v4, 2, v56
	v_max_i32_e32 v4, 8, v4
	v_add_u32_e32 v4, -8, v4
	v_min_u32_e32 v4, 0xffff, v4
	v_mul_u32_u24_e32 v208, 0xe00, v4
	v_lshl_add_u64 v[4:5], s[100:101], 0, v[208:209]
	v_lshl_add_u64 v[4:5], v[4:5], 0, v[130:131]
	global_load_dwordx4 v[4:7], v[4:5], off offset:1536
	v_add_u32_e32 v8, 4, v56
	v_max_i32_e32 v8, 8, v8
	v_add_u32_e32 v8, -8, v8
	v_min_u32_e32 v8, 0xffff, v8
	v_mul_u32_u24_e32 v208, 0xe00, v8
	v_lshl_add_u64 v[8:9], s[100:101], 0, v[208:209]
	v_lshl_add_u64 v[8:9], v[8:9], 0, v[130:131]
	global_load_dwordx4 v[8:11], v[8:9], off offset:1536
	v_add_u32_e32 v12, 6, v56
	v_max_i32_e32 v12, 8, v12
	v_add_u32_e32 v12, -8, v12
	v_min_u32_e32 v12, 0xffff, v12
	v_mul_u32_u24_e32 v208, 0xe00, v12
	v_lshl_add_u64 v[12:13], s[100:101], 0, v[208:209]
	v_lshl_add_u64 v[12:13], v[12:13], 0, v[130:131]
	global_load_dwordx4 v[12:15], v[12:13], off offset:1536
	v_add_u32_e32 v16, 8, v56
	v_max_i32_e32 v16, 8, v16
	v_add_u32_e32 v16, -8, v16
	v_min_u32_e32 v16, 0xffff, v16
	v_mul_u32_u24_e32 v208, 0xe00, v16
	v_lshl_add_u64 v[16:17], s[100:101], 0, v[208:209]
	v_lshl_add_u64 v[16:17], v[16:17], 0, v[130:131]
	global_load_dwordx4 v[16:19], v[16:17], off offset:1536
	v_add_u32_e32 v20, 10, v56
	v_max_i32_e32 v20, 8, v20
	v_add_u32_e32 v20, -8, v20
	v_min_u32_e32 v20, 0xffff, v20
	v_mul_u32_u24_e32 v208, 0xe00, v20
	v_lshl_add_u64 v[20:21], s[100:101], 0, v[208:209]
	v_lshl_add_u64 v[20:21], v[20:21], 0, v[130:131]
	global_load_dwordx4 v[20:23], v[20:21], off offset:1536
	v_add_u32_e32 v24, 12, v56
	v_max_i32_e32 v24, 8, v24
	v_add_u32_e32 v24, -8, v24
	v_min_u32_e32 v24, 0xffff, v24
	v_mul_u32_u24_e32 v208, 0xe00, v24
	v_lshl_add_u64 v[24:25], s[100:101], 0, v[208:209]
	v_lshl_add_u64 v[24:25], v[24:25], 0, v[130:131]
	global_load_dwordx4 v[24:27], v[24:25], off offset:1536
	v_add_u32_e32 v28, 14, v56
	v_max_i32_e32 v28, 8, v28
	v_add_u32_e32 v28, -8, v28
	v_min_u32_e32 v28, 0xffff, v28
	v_mul_u32_u24_e32 v208, 0xe00, v28
	v_lshl_add_u64 v[28:29], s[100:101], 0, v[208:209]
	v_lshl_add_u64 v[28:29], v[28:29], 0, v[130:131]
	global_load_dwordx4 v[28:31], v[28:29], off offset:1536
	v_add_u32_e32 v32, 16, v56
	v_max_i32_e32 v32, 8, v32
	v_add_u32_e32 v32, -8, v32
	v_min_u32_e32 v32, 0xffff, v32
	v_mul_u32_u24_e32 v208, 0xe00, v32
	v_lshl_add_u64 v[32:33], s[100:101], 0, v[208:209]
	v_lshl_add_u64 v[32:33], v[32:33], 0, v[130:131]
	global_load_dwordx4 v[32:35], v[32:33], off offset:1536
	v_add_u32_e32 v36, 18, v56
	v_max_i32_e32 v36, 8, v36
	v_add_u32_e32 v36, -8, v36
	v_min_u32_e32 v36, 0xffff, v36
	v_mul_u32_u24_e32 v208, 0xe00, v36
	v_lshl_add_u64 v[36:37], s[100:101], 0, v[208:209]
	v_lshl_add_u64 v[36:37], v[36:37], 0, v[130:131]
	global_load_dwordx4 v[36:39], v[36:37], off offset:1536
	v_add_u32_e32 v40, 20, v56
	v_max_i32_e32 v40, 8, v40
	v_add_u32_e32 v40, -8, v40
	v_min_u32_e32 v40, 0xffff, v40
	v_mul_u32_u24_e32 v208, 0xe00, v40
	v_lshl_add_u64 v[40:41], s[100:101], 0, v[208:209]
	v_lshl_add_u64 v[40:41], v[40:41], 0, v[130:131]
	global_load_dwordx4 v[40:43], v[40:41], off offset:1536
	v_add_u32_e32 v44, 22, v56
	v_max_i32_e32 v44, 8, v44
	v_add_u32_e32 v44, -8, v44
	v_min_u32_e32 v44, 0xffff, v44
	v_mul_u32_u24_e32 v208, 0xe00, v44
	v_lshl_add_u64 v[44:45], s[100:101], 0, v[208:209]
	v_lshl_add_u64 v[44:45], v[44:45], 0, v[130:131]
	global_load_dwordx4 v[44:47], v[44:45], off offset:1536
	v_add_u32_e32 v48, 24, v56
	v_max_i32_e32 v48, 8, v48
	v_add_u32_e32 v48, -8, v48
	v_min_u32_e32 v48, 0xffff, v48
	v_mul_u32_u24_e32 v208, 0xe00, v48
	v_lshl_add_u64 v[48:49], s[100:101], 0, v[208:209]
	v_lshl_add_u64 v[48:49], v[48:49], 0, v[130:131]
	global_load_dwordx4 v[48:51], v[48:49], off offset:1536
	v_add_u32_e32 v52, 26, v56
	v_max_i32_e32 v52, 8, v52
	v_add_u32_e32 v52, -8, v52
	v_min_u32_e32 v52, 0xffff, v52
	v_mul_u32_u24_e32 v208, 0xe00, v52
	v_lshl_add_u64 v[52:53], s[100:101], 0, v[208:209]
	v_lshl_add_u64 v[52:53], v[52:53], 0, v[130:131]
	global_load_dwordx4 v[52:55], v[52:53], off offset:1536
	v_add_u32_e32 v58, 28, v56
	v_max_i32_e32 v58, 8, v58
	v_add_u32_e32 v58, -8, v58
	v_min_u32_e32 v58, 0xffff, v58
	v_mul_u32_u24_e32 v208, 0xe00, v58
	v_lshl_add_u64 v[58:59], s[100:101], 0, v[208:209]
	v_lshl_add_u64 v[58:59], v[58:59], 0, v[130:131]
	global_load_dwordx4 v[58:61], v[58:59], off offset:1536
	v_add_u32_e32 v62, 30, v56
	v_max_i32_e32 v62, 8, v62
	v_add_u32_e32 v62, -8, v62
	v_min_u32_e32 v62, 0xffff, v62
	v_mul_u32_u24_e32 v208, 0xe00, v62
	v_lshl_add_u64 v[62:63], s[100:101], 0, v[208:209]
	v_lshl_add_u64 v[62:63], v[62:63], 0, v[130:131]
	global_load_dwordx4 v[62:65], v[62:63], off offset:1536
	s_cmpk_lt_u32 s18, 0x2000
	s_cselect_b64 vcc, -1, 0
	s_waitcnt vmcnt(15)
	v_cndmask_b32_e32 v3, 0, v3, vcc
	v_cndmask_b32_e32 v2, 0, v2, vcc
	v_cndmask_b32_e32 v1, 0, v1, vcc
	v_cndmask_b32_e32 v0, 0, v0, vcc
	s_waitcnt vmcnt(14)
	v_cndmask_b32_e32 v7, 0, v7, vcc
	v_cndmask_b32_e32 v6, 0, v6, vcc
	v_cndmask_b32_e32 v5, 0, v5, vcc
	v_cndmask_b32_e32 v4, 0, v4, vcc
	s_waitcnt vmcnt(13)
	v_cndmask_b32_e32 v11, 0, v11, vcc
	v_cndmask_b32_e32 v10, 0, v10, vcc
	v_cndmask_b32_e32 v9, 0, v9, vcc
	v_cndmask_b32_e32 v8, 0, v8, vcc
	s_waitcnt vmcnt(12)
	v_cndmask_b32_e32 v15, 0, v15, vcc
	v_cndmask_b32_e32 v14, 0, v14, vcc
	v_cndmask_b32_e32 v13, 0, v13, vcc
	v_cndmask_b32_e32 v12, 0, v12, vcc
	s_cmp_gt_i32 s11, -1
	s_cselect_b64 vcc, -1, 0
	s_waitcnt vmcnt(11)
	v_cndmask_b32_e32 v19, 0, v19, vcc
	v_cndmask_b32_e32 v18, 0, v18, vcc
	v_cndmask_b32_e32 v17, 0, v17, vcc
	v_cndmask_b32_e32 v16, 0, v16, vcc
	v_add_u32_e32 v206, s18, v138
	v_cmp_gt_u32_e32 vcc, s15, v206
	s_waitcnt vmcnt(10)
	s_nop 0
	v_cndmask_b32_e32 v23, 0, v23, vcc
	v_cndmask_b32_e32 v22, 0, v22, vcc
	v_cndmask_b32_e32 v21, 0, v21, vcc
	v_cndmask_b32_e32 v20, 0, v20, vcc
	v_add_u32_e32 v206, s18, v139
	v_cmp_gt_u32_e32 vcc, s15, v206
	s_waitcnt vmcnt(9)
	s_nop 0
	v_cndmask_b32_e32 v27, 0, v27, vcc
	v_cndmask_b32_e32 v26, 0, v26, vcc
	v_cndmask_b32_e32 v25, 0, v25, vcc
	v_cndmask_b32_e32 v24, 0, v24, vcc
	v_add_u32_e32 v206, s18, v140
	v_cmp_gt_u32_e32 vcc, s15, v206
	s_waitcnt vmcnt(8)
	s_nop 0
	v_cndmask_b32_e32 v31, 0, v31, vcc
	v_cndmask_b32_e32 v30, 0, v30, vcc
	v_cndmask_b32_e32 v29, 0, v29, vcc
	v_cndmask_b32_e32 v28, 0, v28, vcc
	v_add_u32_e32 v206, s18, v141
	v_cmp_gt_u32_e32 vcc, s15, v206
	s_waitcnt vmcnt(7)
	s_nop 0
	v_cndmask_b32_e32 v35, 0, v35, vcc
	v_cndmask_b32_e32 v34, 0, v34, vcc
	v_cndmask_b32_e32 v33, 0, v33, vcc
	v_cndmask_b32_e32 v32, 0, v32, vcc
	v_add_u32_e32 v206, s18, v142
	v_cmp_gt_u32_e32 vcc, s15, v206
	s_waitcnt vmcnt(6)
	s_nop 0
	v_cndmask_b32_e32 v39, 0, v39, vcc
	v_cndmask_b32_e32 v38, 0, v38, vcc
	v_cndmask_b32_e32 v37, 0, v37, vcc
	v_cndmask_b32_e32 v36, 0, v36, vcc
	v_add_u32_e32 v206, s18, v143
	v_cmp_gt_u32_e32 vcc, s15, v206
	s_waitcnt vmcnt(5)
	s_nop 0
	v_cndmask_b32_e32 v43, 0, v43, vcc
	v_cndmask_b32_e32 v42, 0, v42, vcc
	v_cndmask_b32_e32 v41, 0, v41, vcc
	v_cndmask_b32_e32 v40, 0, v40, vcc
	v_add_u32_e32 v206, s18, v144
	v_cmp_gt_u32_e32 vcc, s15, v206
	s_waitcnt vmcnt(4)
	s_nop 0
	v_cndmask_b32_e32 v47, 0, v47, vcc
	v_cndmask_b32_e32 v46, 0, v46, vcc
	v_cndmask_b32_e32 v45, 0, v45, vcc
	v_cndmask_b32_e32 v44, 0, v44, vcc
	v_add_u32_e32 v206, s18, v145
	v_cmp_gt_u32_e32 vcc, s15, v206
	s_waitcnt vmcnt(3)
	s_nop 0
	v_cndmask_b32_e32 v51, 0, v51, vcc
	v_cndmask_b32_e32 v50, 0, v50, vcc
	v_cndmask_b32_e32 v49, 0, v49, vcc
	v_cndmask_b32_e32 v48, 0, v48, vcc
	v_add_u32_e32 v206, s18, v146
	v_cmp_gt_u32_e32 vcc, s15, v206
	s_waitcnt vmcnt(2)
	s_nop 0
	v_cndmask_b32_e32 v55, 0, v55, vcc
	v_cndmask_b32_e32 v54, 0, v54, vcc
	v_cndmask_b32_e32 v53, 0, v53, vcc
	v_cndmask_b32_e32 v52, 0, v52, vcc
	v_add_u32_e32 v206, s18, v147
	v_cmp_gt_u32_e32 vcc, s15, v206
	s_waitcnt vmcnt(1)
	s_nop 0
	v_cndmask_b32_e32 v61, 0, v61, vcc
	v_cndmask_b32_e32 v60, 0, v60, vcc
	v_cndmask_b32_e32 v59, 0, v59, vcc
	v_cndmask_b32_e32 v58, 0, v58, vcc
	v_add_u32_e32 v206, s18, v148
	v_cmp_gt_u32_e32 vcc, s15, v206
	s_waitcnt vmcnt(0)
	s_nop 0
	v_cndmask_b32_e32 v65, 0, v65, vcc
	v_cndmask_b32_e32 v64, 0, v64, vcc
	v_cndmask_b32_e32 v63, 0, v63, vcc
	v_cndmask_b32_e32 v62, 0, v62, vcc
	v_or_b32_e32 v56, s11, v136
	ds_write_b128 v150, v[0:3]
	ds_write_b128 v150, v[4:7] offset:1056
	ds_write_b128 v150, v[8:11] offset:2112
	ds_write_b128 v150, v[12:15] offset:3168
	ds_write_b128 v150, v[16:19] offset:4224
	ds_write_b128 v150, v[20:23] offset:5280
	ds_write_b128 v150, v[24:27] offset:6336
	ds_write_b128 v150, v[28:31] offset:7392
	ds_write_b128 v150, v[32:35] offset:8448
	ds_write_b128 v150, v[36:39] offset:9504
	ds_write_b128 v150, v[40:43] offset:10560
	ds_write_b128 v150, v[44:47] offset:11616
	ds_write_b128 v150, v[48:51] offset:12672
	ds_write_b128 v150, v[52:55] offset:13728
	ds_write_b128 v150, v[58:61] offset:14784
	ds_write_b128 v150, v[62:65] offset:15840
	v_add_u32_e32 v0, s9, v136
	v_ashrrev_i32_e32 v1, 31, v0
	v_lshlrev_b64 v[134:135], 11, v[0:1]
	v_max_i32_e32 v0, 1, v56
	v_min_i32_e32 v1, 0x1fff, v56
	v_sub_u32_e32 v0, v1, v0
	v_add_u32_e32 v0, 2, v0
	v_cvt_f32_i32_e32 v0, v0
	s_waitcnt lgkmcnt(0)
	s_add_i32 s9, s9, s17
	s_cmpk_lt_i32 s0, 0x1000
	v_div_scale_f32 v1, s[18:19], v0, v0, 1.0
	v_rcp_f32_e32 v2, v1
	s_nop 0
	v_fma_f32 v3, -v1, v2, 1.0
	v_fmac_f32_e32 v2, v3, v2
	v_div_scale_f32 v3, vcc, 1.0, v0, 1.0
	v_mul_f32_e32 v4, v3, v2
	v_fma_f32 v5, -v1, v4, v3
	v_fmac_f32_e32 v4, v5, v2
	v_fma_f32 v1, -v1, v4, v3
	v_div_fmas_f32 v1, v1, v2, v4
	v_div_fixup_f32 v20, v1, v0, 1.0
	ds_read_b128 v[0:3], v149 offset:3696
	s_waitcnt lgkmcnt(0)
	v_lshlrev_b32_e32 v4, 16, v0
	v_and_b32_e32 v0, 0xffff0000, v0
	v_lshlrev_b32_e32 v5, 16, v1
	v_and_b32_e32 v1, 0xffff0000, v1
	v_lshlrev_b32_e32 v6, 16, v2
	v_and_b32_e32 v2, 0xffff0000, v2
	v_lshlrev_b32_e32 v7, 16, v3
	v_and_b32_e32 v3, 0xffff0000, v3
	v_add_f32_e32 v8, 0, v0
	v_add_f32_e32 v9, 0, v1
	v_add_f32_e32 v10, 0, v2
	v_add_f32_e32 v11, 0, v3
	ds_read_b128 v[0:3], v149 offset:4224
	v_add_f32_e32 v4, 0, v4
	v_add_f32_e32 v5, 0, v5
	v_add_f32_e32 v6, 0, v6
	v_add_f32_e32 v7, 0, v7
	s_waitcnt lgkmcnt(0)
	v_lshlrev_b32_e32 v12, 16, v0
	v_and_b32_e32 v0, 0xffff0000, v0
	v_lshlrev_b32_e32 v13, 16, v1
	v_and_b32_e32 v1, 0xffff0000, v1
	v_lshlrev_b32_e32 v14, 16, v2
	v_and_b32_e32 v2, 0xffff0000, v2
	v_lshlrev_b32_e32 v15, 16, v3
	v_and_b32_e32 v3, 0xffff0000, v3
	v_add_f32_e32 v8, v8, v0
	v_add_f32_e32 v9, v9, v1
	v_add_f32_e32 v10, v10, v2
	v_add_f32_e32 v11, v11, v3
	v_add_f32_e32 v4, v4, v12
	v_add_f32_e32 v5, v5, v13
	v_add_f32_e32 v6, v6, v14
	v_add_f32_e32 v7, v7, v15
	v_fma_f32 v0, v20, v8, -v0
	v_fma_f32 v1, v20, v9, -v1
	v_fma_f32 v2, v20, v10, -v2
	v_fma_f32 v3, v20, v11, -v3
	v_fma_f32 v4, v20, v4, -v12
	v_fma_f32 v5, v20, v5, -v13
	v_fma_f32 v6, v20, v6, -v14
	v_fma_f32 v7, v20, v7, -v15
	v_cvt_pk_bf16_f32 v0, v4, v0
	v_cvt_pk_bf16_f32 v1, v5, v1
	v_cvt_pk_bf16_f32 v2, v6, v2
	v_cvt_pk_bf16_f32 v3, v7, v3
	s_waitcnt vmcnt(2)
	v_mfma_f32_16x16x32_bf16 v[16:19], v[90:93], v[0:3], 0
	s_waitcnt vmcnt(2)
	v_mfma_f32_16x16x32_bf16 v[4:7], v[94:97], v[0:3], 0
	s_waitcnt vmcnt(1)
	v_mfma_f32_16x16x32_bf16 v[8:11], v[106:109], v[0:3], 0
	s_waitcnt vmcnt(0)
	v_mfma_f32_16x16x32_bf16 v[0:3], v[110:113], v[0:3], 0
	global_load_dwordx4 v[90:93], v[86:87], off
	global_load_dwordx4 v[94:97], v[82:83], off
	global_load_dwordx4 v[106:109], v[84:85], off
	global_load_dwordx4 v[110:113], v[88:89], off
	ds_read_b128 v[12:15], v149 offset:3760
	s_waitcnt lgkmcnt(0)
	v_lshlrev_b32_e32 v21, 16, v12
	v_and_b32_e32 v12, 0xffff0000, v12
	v_lshlrev_b32_e32 v22, 16, v13
	v_and_b32_e32 v13, 0xffff0000, v13
	v_lshlrev_b32_e32 v23, 16, v14
	v_and_b32_e32 v14, 0xffff0000, v14
	v_lshlrev_b32_e32 v24, 16, v15
	v_and_b32_e32 v15, 0xffff0000, v15
	v_add_f32_e32 v25, 0, v12
	v_add_f32_e32 v26, 0, v13
	v_add_f32_e32 v27, 0, v14
	v_add_f32_e32 v28, 0, v15
	ds_read_b128 v[12:15], v149 offset:4288
	v_add_f32_e32 v21, 0, v21
	v_add_f32_e32 v22, 0, v22
	v_add_f32_e32 v23, 0, v23
	v_add_f32_e32 v24, 0, v24
	s_waitcnt lgkmcnt(0)
	v_lshlrev_b32_e32 v29, 16, v12
	v_and_b32_e32 v12, 0xffff0000, v12
	v_lshlrev_b32_e32 v30, 16, v13
	v_and_b32_e32 v13, 0xffff0000, v13
	v_lshlrev_b32_e32 v31, 16, v14
	v_and_b32_e32 v14, 0xffff0000, v14
	v_lshlrev_b32_e32 v32, 16, v15
	v_and_b32_e32 v15, 0xffff0000, v15
	v_add_f32_e32 v21, v21, v29
	v_add_f32_e32 v25, v25, v12
	v_add_f32_e32 v22, v22, v30
	v_add_f32_e32 v26, v26, v13
	v_add_f32_e32 v23, v23, v31
	v_add_f32_e32 v27, v27, v14
	v_add_f32_e32 v28, v28, v15
	v_add_f32_e32 v24, v24, v32
	v_fma_f32 v21, v20, v21, -v29
	v_fma_f32 v12, v20, v25, -v12
	v_fma_f32 v22, v20, v22, -v30
	v_fma_f32 v13, v20, v26, -v13
	v_fma_f32 v23, v20, v23, -v31
	v_fma_f32 v14, v20, v27, -v14
	v_fma_f32 v15, v20, v28, -v15
	v_fma_f32 v24, v20, v24, -v32
	v_cvt_pk_bf16_f32 v20, v21, v12
	v_cvt_pk_bf16_f32 v21, v22, v13
	v_cvt_pk_bf16_f32 v22, v23, v14
	v_cvt_pk_bf16_f32 v23, v24, v15
	s_waitcnt vmcnt(0)
	v_mfma_f32_16x16x32_bf16 v[12:15], v[166:169], v[20:23], v[4:7]
	s_nop 2
	s_waitcnt vmcnt(0)
	v_mfma_f32_16x16x32_bf16 v[8:11], v[170:173], v[20:23], v[8:11]
	s_waitcnt vmcnt(0)
	v_mfma_f32_16x16x32_bf16 v[4:7], v[174:177], v[20:23], v[16:19]
	s_nop 2
	s_waitcnt vmcnt(0)
	v_mfma_f32_16x16x32_bf16 v[0:3], v[178:181], v[20:23], v[0:3]
	v_max_i32_e32 v16, 2, v56
	v_min_i32_e32 v17, 0x1ffe, v56
	v_sub_u32_e32 v16, v17, v16
	v_add_u32_e32 v16, 4, v16
	v_cvt_f32_i32_e32 v16, v16
	v_div_scale_f32 v17, s[18:19], v16, v16, 1.0
	v_rcp_f32_e32 v18, v17
	s_nop 0
	v_fma_f32 v19, -v17, v18, 1.0
	v_fmac_f32_e32 v18, v19, v18
	v_div_scale_f32 v19, vcc, 1.0, v16, 1.0
	v_mul_f32_e32 v20, v19, v18
	v_fma_f32 v21, -v17, v20, v19
	v_fmac_f32_e32 v20, v21, v18
	v_fma_f32 v17, -v17, v20, v19
	v_div_fmas_f32 v17, v17, v18, v20
	v_div_fixup_f32 v36, v17, v16, 1.0
	ds_read_b128 v[16:19], v149 offset:3296
	s_waitcnt lgkmcnt(0)
	v_lshlrev_b32_e32 v20, 16, v16
	v_and_b32_e32 v16, 0xffff0000, v16
	v_lshlrev_b32_e32 v21, 16, v17
	v_and_b32_e32 v17, 0xffff0000, v17
	v_lshlrev_b32_e32 v22, 16, v18
	v_and_b32_e32 v18, 0xffff0000, v18
	v_lshlrev_b32_e32 v23, 16, v19
	v_and_b32_e32 v19, 0xffff0000, v19
	v_add_f32_e32 v24, 0, v16
	v_add_f32_e32 v25, 0, v17
	v_add_f32_e32 v26, 0, v18
	v_add_f32_e32 v27, 0, v19
	ds_read_b128 v[16:19], v149 offset:3824
	v_add_f32_e32 v20, 0, v20
	v_add_f32_e32 v21, 0, v21
	v_add_f32_e32 v22, 0, v22
	v_add_f32_e32 v23, 0, v23
	s_waitcnt lgkmcnt(0)
	v_lshlrev_b32_e32 v28, 16, v16
	v_and_b32_e32 v16, 0xffff0000, v16
	v_lshlrev_b32_e32 v29, 16, v17
	v_and_b32_e32 v17, 0xffff0000, v17
	v_lshlrev_b32_e32 v30, 16, v18
	v_and_b32_e32 v18, 0xffff0000, v18
	v_lshlrev_b32_e32 v31, 16, v19
	v_and_b32_e32 v19, 0xffff0000, v19
	v_add_f32_e32 v24, v24, v16
	v_add_f32_e32 v25, v25, v17
	v_add_f32_e32 v26, v26, v18
	v_add_f32_e32 v27, v27, v19
	ds_read_b128 v[16:19], v149 offset:4352
	v_add_f32_e32 v20, v20, v28
	v_add_f32_e32 v21, v21, v29
	v_add_f32_e32 v22, v22, v30
	v_add_f32_e32 v23, v23, v31
	s_waitcnt lgkmcnt(0)
	v_lshlrev_b32_e32 v28, 16, v16
	v_and_b32_e32 v29, 0xffff0000, v16
	v_lshlrev_b32_e32 v30, 16, v17
	v_and_b32_e32 v31, 0xffff0000, v17
	v_lshlrev_b32_e32 v32, 16, v18
	v_and_b32_e32 v33, 0xffff0000, v18
	v_lshlrev_b32_e32 v34, 16, v19
	v_and_b32_e32 v35, 0xffff0000, v19
	ds_read_b128 v[16:19], v149 offset:4880
	v_add_f32_e32 v24, v24, v29
	v_add_f32_e32 v25, v25, v31
	v_add_f32_e32 v26, v26, v33
	v_add_f32_e32 v27, v27, v35
	s_waitcnt lgkmcnt(0)
	v_lshlrev_b32_e32 v37, 16, v16
	v_and_b32_e32 v16, 0xffff0000, v16
	v_lshlrev_b32_e32 v38, 16, v17
	v_and_b32_e32 v17, 0xffff0000, v17
	v_lshlrev_b32_e32 v39, 16, v18
	v_and_b32_e32 v18, 0xffff0000, v18
	v_lshlrev_b32_e32 v40, 16, v19
	v_and_b32_e32 v19, 0xffff0000, v19
	v_add_f32_e32 v20, v20, v28
	v_add_f32_e32 v21, v21, v30
	v_add_f32_e32 v22, v22, v32
	v_add_f32_e32 v23, v23, v34
	v_add_f32_e32 v16, v24, v16
	v_add_f32_e32 v17, v25, v17
	v_add_f32_e32 v18, v26, v18
	v_add_f32_e32 v19, v27, v19
	v_add_f32_e32 v20, v20, v37
	v_add_f32_e32 v21, v21, v38
	v_add_f32_e32 v22, v22, v39
	v_add_f32_e32 v23, v23, v40
	v_fma_f32 v16, v36, v16, -v29
	v_fma_f32 v17, v36, v17, -v31
	v_fma_f32 v18, v36, v18, -v33
	v_fma_f32 v19, v36, v19, -v35
	v_fma_f32 v20, v36, v20, -v28
	v_fma_f32 v21, v36, v21, -v30
	v_fma_f32 v22, v36, v22, -v32
	v_fma_f32 v23, v36, v23, -v34
	v_cvt_pk_bf16_f32 v16, v20, v16
	v_cvt_pk_bf16_f32 v17, v21, v17
	v_cvt_pk_bf16_f32 v18, v22, v18
	v_cvt_pk_bf16_f32 v19, v23, v19
	s_waitcnt vmcnt(2)
	v_mfma_f32_16x16x32_bf16 v[32:35], v[90:93], v[16:19], 0
	s_waitcnt vmcnt(2)
	v_mfma_f32_16x16x32_bf16 v[20:23], v[94:97], v[16:19], 0
	s_waitcnt vmcnt(1)
	v_mfma_f32_16x16x32_bf16 v[24:27], v[106:109], v[16:19], 0
	s_waitcnt vmcnt(0)
	v_mfma_f32_16x16x32_bf16 v[16:19], v[110:113], v[16:19], 0
	global_load_dwordx4 v[90:93], v[98:99], off
	global_load_dwordx4 v[94:97], v[100:101], off
	global_load_dwordx4 v[106:109], v[102:103], off
	global_load_dwordx4 v[110:113], v[104:105], off
	ds_read_b128 v[28:31], v149 offset:3360
	s_waitcnt lgkmcnt(0)
	v_lshlrev_b32_e32 v37, 16, v28
	v_and_b32_e32 v28, 0xffff0000, v28
	v_lshlrev_b32_e32 v38, 16, v29
	v_and_b32_e32 v29, 0xffff0000, v29
	v_lshlrev_b32_e32 v39, 16, v30
	v_and_b32_e32 v30, 0xffff0000, v30
	v_lshlrev_b32_e32 v40, 16, v31
	v_and_b32_e32 v31, 0xffff0000, v31
	v_add_f32_e32 v41, 0, v28
	v_add_f32_e32 v42, 0, v29
	v_add_f32_e32 v43, 0, v30
	v_add_f32_e32 v44, 0, v31
	ds_read_b128 v[28:31], v149 offset:3888
	v_add_f32_e32 v37, 0, v37
	v_add_f32_e32 v38, 0, v38
	v_add_f32_e32 v39, 0, v39
	v_add_f32_e32 v40, 0, v40
	s_waitcnt lgkmcnt(0)
	v_lshlrev_b32_e32 v45, 16, v28
	v_and_b32_e32 v28, 0xffff0000, v28
	v_lshlrev_b32_e32 v46, 16, v29
	v_and_b32_e32 v29, 0xffff0000, v29
	v_lshlrev_b32_e32 v47, 16, v30
	v_and_b32_e32 v30, 0xffff0000, v30
	v_lshlrev_b32_e32 v48, 16, v31
	v_and_b32_e32 v31, 0xffff0000, v31
	v_add_f32_e32 v41, v41, v28
	v_add_f32_e32 v42, v42, v29
	v_add_f32_e32 v43, v43, v30
	v_add_f32_e32 v44, v44, v31
	ds_read_b128 v[28:31], v149 offset:4416
	v_add_f32_e32 v37, v37, v45
	v_add_f32_e32 v38, v38, v46
	v_add_f32_e32 v39, v39, v47
	v_add_f32_e32 v40, v40, v48
	s_waitcnt lgkmcnt(0)
	v_lshlrev_b32_e32 v45, 16, v28
	v_and_b32_e32 v46, 0xffff0000, v28
	v_lshlrev_b32_e32 v47, 16, v29
	v_and_b32_e32 v48, 0xffff0000, v29
	v_lshlrev_b32_e32 v49, 16, v30
	v_and_b32_e32 v50, 0xffff0000, v30
	v_lshlrev_b32_e32 v51, 16, v31
	v_and_b32_e32 v52, 0xffff0000, v31
	ds_read_b128 v[28:31], v149 offset:4944
	v_add_f32_e32 v37, v37, v45
	v_add_f32_e32 v41, v41, v46
	v_add_f32_e32 v38, v38, v47
	v_add_f32_e32 v42, v42, v48
	v_add_f32_e32 v39, v39, v49
	v_add_f32_e32 v43, v43, v50
	v_add_f32_e32 v44, v44, v52
	s_waitcnt lgkmcnt(0)
	v_lshlrev_b32_e32 v53, 16, v28
	v_and_b32_e32 v28, 0xffff0000, v28
	v_lshlrev_b32_e32 v54, 16, v29
	v_and_b32_e32 v29, 0xffff0000, v29
	v_lshlrev_b32_e32 v55, 16, v30
	v_and_b32_e32 v30, 0xffff0000, v30
	v_lshlrev_b32_e32 v57, 16, v31
	v_and_b32_e32 v31, 0xffff0000, v31
	v_add_f32_e32 v40, v40, v51
	v_add_f32_e32 v37, v37, v53
	v_add_f32_e32 v28, v41, v28
	v_add_f32_e32 v38, v38, v54
	v_add_f32_e32 v29, v42, v29
	v_add_f32_e32 v39, v39, v55
	v_add_f32_e32 v30, v43, v30
	v_add_f32_e32 v31, v44, v31
	v_add_f32_e32 v40, v40, v57
	v_fma_f32 v37, v36, v37, -v45
	v_fma_f32 v28, v36, v28, -v46
	v_fma_f32 v38, v36, v38, -v47
	v_fma_f32 v29, v36, v29, -v48
	v_fma_f32 v39, v36, v39, -v49
	v_fma_f32 v30, v36, v30, -v50
	v_fma_f32 v31, v36, v31, -v52
	v_fma_f32 v40, v36, v40, -v51
	v_cvt_pk_bf16_f32 v36, v37, v28
	v_cvt_pk_bf16_f32 v37, v38, v29
	v_cvt_pk_bf16_f32 v38, v39, v30
	v_cvt_pk_bf16_f32 v39, v40, v31
	s_waitcnt vmcnt(0)
	v_mfma_f32_16x16x32_bf16 v[28:31], v[182:185], v[36:39], v[20:23]
	s_nop 2
	s_waitcnt vmcnt(0)
	v_mfma_f32_16x16x32_bf16 v[24:27], v[186:189], v[36:39], v[24:27]
	s_waitcnt vmcnt(0)
	v_mfma_f32_16x16x32_bf16 v[20:23], v[190:193], v[36:39], v[32:35]
	s_nop 2
	s_waitcnt vmcnt(0)
	v_mfma_f32_16x16x32_bf16 v[16:19], v[194:197], v[36:39], v[16:19]
	v_max_i32_e32 v32, 4, v56
	v_min_i32_e32 v33, 0x1ffc, v56
	v_sub_u32_e32 v32, v33, v32
	v_add_u32_e32 v32, 8, v32
	v_cvt_f32_i32_e32 v32, v32
	v_div_scale_f32 v33, s[18:19], v32, v32, 1.0
	v_rcp_f32_e32 v34, v33
	s_nop 0
	v_fma_f32 v35, -v33, v34, 1.0
	v_fmac_f32_e32 v34, v35, v34
	v_div_scale_f32 v35, vcc, 1.0, v32, 1.0
	v_mul_f32_e32 v36, v35, v34
	v_fma_f32 v37, -v33, v36, v35
	v_fmac_f32_e32 v36, v37, v34
	v_fma_f32 v33, -v33, v36, v35
	v_div_fmas_f32 v33, v33, v34, v36
	v_div_fixup_f32 v40, v33, v32, 1.0
	ds_read_b128 v[32:35], v149 offset:2368
	s_waitcnt lgkmcnt(0)
	v_lshlrev_b32_e32 v36, 16, v32
	v_and_b32_e32 v32, 0xffff0000, v32
	v_lshlrev_b32_e32 v37, 16, v33
	v_and_b32_e32 v33, 0xffff0000, v33
	v_lshlrev_b32_e32 v38, 16, v34
	v_and_b32_e32 v34, 0xffff0000, v34
	v_lshlrev_b32_e32 v39, 16, v35
	v_and_b32_e32 v35, 0xffff0000, v35
	v_add_f32_e32 v41, 0, v32
	v_add_f32_e32 v42, 0, v33
	v_add_f32_e32 v43, 0, v34
	v_add_f32_e32 v44, 0, v35
	ds_read_b128 v[32:35], v149 offset:2896
	v_add_f32_e32 v36, 0, v36
	v_add_f32_e32 v37, 0, v37
	v_add_f32_e32 v38, 0, v38
	v_add_f32_e32 v39, 0, v39
	s_waitcnt lgkmcnt(0)
	v_lshlrev_b32_e32 v45, 16, v32
	v_and_b32_e32 v32, 0xffff0000, v32
	v_lshlrev_b32_e32 v46, 16, v33
	v_and_b32_e32 v33, 0xffff0000, v33
	v_lshlrev_b32_e32 v47, 16, v34
	v_and_b32_e32 v34, 0xffff0000, v34
	v_lshlrev_b32_e32 v48, 16, v35
	v_and_b32_e32 v35, 0xffff0000, v35
	v_add_f32_e32 v41, v41, v32
	v_add_f32_e32 v42, v42, v33
	v_add_f32_e32 v43, v43, v34
	v_add_f32_e32 v44, v44, v35
	ds_read_b128 v[32:35], v149 offset:3424
	v_add_f32_e32 v36, v36, v45
	v_add_f32_e32 v37, v37, v46
	v_add_f32_e32 v38, v38, v47
	v_add_f32_e32 v39, v39, v48
	s_waitcnt lgkmcnt(0)
	v_lshlrev_b32_e32 v45, 16, v32
	v_and_b32_e32 v32, 0xffff0000, v32
	v_lshlrev_b32_e32 v46, 16, v33
	v_and_b32_e32 v33, 0xffff0000, v33
	v_lshlrev_b32_e32 v47, 16, v34
	v_and_b32_e32 v34, 0xffff0000, v34
	v_lshlrev_b32_e32 v48, 16, v35
	v_and_b32_e32 v35, 0xffff0000, v35
	v_add_f32_e32 v41, v41, v32
	v_add_f32_e32 v42, v42, v33
	v_add_f32_e32 v43, v43, v34
	v_add_f32_e32 v44, v44, v35
	ds_read_b128 v[32:35], v149 offset:3952
	v_add_f32_e32 v36, v36, v45
	v_add_f32_e32 v37, v37, v46
	v_add_f32_e32 v38, v38, v47
	v_add_f32_e32 v39, v39, v48
	s_waitcnt lgkmcnt(0)
	v_lshlrev_b32_e32 v45, 16, v32
	v_lshlrev_b32_e32 v46, 16, v33
	v_lshlrev_b32_e32 v47, 16, v34
	v_lshlrev_b32_e32 v48, 16, v35
	v_add_f32_e32 v45, v36, v45
	v_add_f32_e32 v46, v37, v46
	v_add_f32_e32 v47, v38, v47
	v_add_f32_e32 v48, v39, v48
	ds_read_b128 v[36:39], v149 offset:4480
	v_and_b32_e32 v32, 0xffff0000, v32
	v_and_b32_e32 v33, 0xffff0000, v33
	v_and_b32_e32 v34, 0xffff0000, v34
	v_and_b32_e32 v35, 0xffff0000, v35
	v_add_f32_e32 v41, v41, v32
	v_add_f32_e32 v42, v42, v33
	v_add_f32_e32 v43, v43, v34
	v_add_f32_e32 v44, v44, v35
	s_waitcnt lgkmcnt(0)
	v_lshlrev_b32_e32 v32, 16, v36
	v_and_b32_e32 v33, 0xffff0000, v36
	v_lshlrev_b32_e32 v34, 16, v37
	v_and_b32_e32 v35, 0xffff0000, v37
	v_lshlrev_b32_e32 v36, 16, v38
	v_and_b32_e32 v37, 0xffff0000, v38
	v_lshlrev_b32_e32 v38, 16, v39
	v_and_b32_e32 v39, 0xffff0000, v39
	v_add_f32_e32 v49, v45, v32
	v_add_f32_e32 v50, v42, v35
	v_add_f32_e32 v51, v43, v37
	v_add_f32_e32 v52, v44, v39
	ds_read_b128 v[42:45], v149 offset:5008
	v_add_f32_e32 v41, v41, v33
	v_add_f32_e32 v46, v46, v34
	v_add_f32_e32 v47, v47, v36
	v_add_f32_e32 v48, v48, v38
	s_waitcnt lgkmcnt(0)
	v_lshlrev_b32_e32 v53, 16, v42
	v_and_b32_e32 v42, 0xffff0000, v42
	v_lshlrev_b32_e32 v54, 16, v43
	v_and_b32_e32 v43, 0xffff0000, v43
	v_lshlrev_b32_e32 v55, 16, v44
	v_and_b32_e32 v44, 0xffff0000, v44
	v_lshlrev_b32_e32 v57, 16, v45
	v_and_b32_e32 v45, 0xffff0000, v45
	v_add_f32_e32 v49, v49, v53
	v_add_f32_e32 v53, v41, v42
	v_add_f32_e32 v50, v50, v43
	v_add_f32_e32 v51, v51, v44
	v_add_f32_e32 v52, v52, v45
	ds_read_b128 v[42:45], v149 offset:5536
	v_add_f32_e32 v46, v46, v54
	v_add_f32_e32 v47, v47, v55
	v_add_f32_e32 v48, v48, v57
	s_waitcnt lgkmcnt(0)
	v_lshlrev_b32_e32 v41, 16, v42
	v_and_b32_e32 v42, 0xffff0000, v42
	v_lshlrev_b32_e32 v54, 16, v43
	v_and_b32_e32 v55, 0xffff0000, v43
	v_lshlrev_b32_e32 v57, 16, v44
	v_and_b32_e32 v58, 0xffff0000, v44
	v_lshlrev_b32_e32 v59, 16, v45
	v_and_b32_e32 v60, 0xffff0000, v45
	v_add_f32_e32 v42, v53, v42
	v_add_f32_e32 v43, v46, v54
	v_add_f32_e32 v44, v50, v55
	v_add_f32_e32 v45, v47, v57
	v_add_f32_e32 v46, v51, v58
	v_add_f32_e32 v47, v48, v59
	v_add_f32_e32 v48, v52, v60
	ds_read_b128 v[50:53], v149 offset:6064
	v_add_f32_e32 v41, v49, v41
	s_waitcnt lgkmcnt(0)
	v_lshlrev_b32_e32 v49, 16, v50
	v_and_b32_e32 v50, 0xffff0000, v50
	v_lshlrev_b32_e32 v54, 16, v51
	v_and_b32_e32 v51, 0xffff0000, v51
	v_lshlrev_b32_e32 v55, 16, v52
	v_and_b32_e32 v52, 0xffff0000, v52
	v_lshlrev_b32_e32 v57, 16, v53
	v_and_b32_e32 v53, 0xffff0000, v53
	v_add_f32_e32 v41, v41, v49
	v_add_f32_e32 v42, v42, v50
	v_add_f32_e32 v43, v43, v54
	v_add_f32_e32 v44, v44, v51
	v_add_f32_e32 v45, v45, v55
	v_add_f32_e32 v46, v46, v52
	v_add_f32_e32 v47, v47, v57
	v_add_f32_e32 v48, v48, v53
	v_fma_f32 v32, v40, v41, -v32
	v_fma_f32 v33, v40, v42, -v33
	v_fma_f32 v34, v40, v43, -v34
	v_fma_f32 v35, v40, v44, -v35
	v_fma_f32 v36, v40, v45, -v36
	v_fma_f32 v37, v40, v46, -v37
	v_fma_f32 v38, v40, v47, -v38
	v_fma_f32 v39, v40, v48, -v39
	v_cvt_pk_bf16_f32 v42, v32, v33
	v_cvt_pk_bf16_f32 v43, v34, v35
	v_cvt_pk_bf16_f32 v44, v36, v37
	v_cvt_pk_bf16_f32 v45, v38, v39
	s_waitcnt vmcnt(3)
	v_mfma_f32_16x16x32_bf16 v[32:35], v[90:93], v[42:45], 0
	s_waitcnt vmcnt(2)
	v_mfma_f32_16x16x32_bf16 v[36:39], v[94:97], v[42:45], 0
	s_waitcnt vmcnt(1)
	v_mfma_f32_16x16x32_bf16 v[48:51], v[106:109], v[42:45], 0
	s_waitcnt vmcnt(0)
	v_mfma_f32_16x16x32_bf16 v[52:55], v[110:113], v[42:45], 0
	global_load_dwordx4 v[90:93], v[114:115], off
	global_load_dwordx4 v[94:97], v[116:117], off
	global_load_dwordx4 v[106:109], v[118:119], off
	global_load_dwordx4 v[110:113], v[120:121], off
	ds_read_b128 v[42:45], v149 offset:2432
	s_waitcnt lgkmcnt(0)
	v_lshlrev_b32_e32 v41, 16, v42
	v_and_b32_e32 v42, 0xffff0000, v42
	v_lshlrev_b32_e32 v46, 16, v43
	v_and_b32_e32 v43, 0xffff0000, v43
	v_lshlrev_b32_e32 v47, 16, v44
	v_and_b32_e32 v44, 0xffff0000, v44
	v_lshlrev_b32_e32 v57, 16, v45
	v_and_b32_e32 v45, 0xffff0000, v45
	v_add_f32_e32 v58, 0, v42
	v_add_f32_e32 v59, 0, v43
	v_add_f32_e32 v60, 0, v44
	v_add_f32_e32 v61, 0, v45
	ds_read_b128 v[42:45], v149 offset:2960
	v_add_f32_e32 v41, 0, v41
	v_add_f32_e32 v46, 0, v46
	v_add_f32_e32 v47, 0, v47
	v_add_f32_e32 v57, 0, v57
	s_waitcnt lgkmcnt(0)
	v_lshlrev_b32_e32 v62, 16, v42
	v_and_b32_e32 v42, 0xffff0000, v42
	v_lshlrev_b32_e32 v63, 16, v43
	v_and_b32_e32 v43, 0xffff0000, v43
	v_lshlrev_b32_e32 v64, 16, v44
	v_and_b32_e32 v44, 0xffff0000, v44
	v_lshlrev_b32_e32 v65, 16, v45
	v_and_b32_e32 v45, 0xffff0000, v45
	v_add_f32_e32 v58, v58, v42
	v_add_f32_e32 v59, v59, v43
	v_add_f32_e32 v60, v60, v44
	v_add_f32_e32 v61, v61, v45
	ds_read_b128 v[42:45], v149 offset:3488
	v_add_f32_e32 v41, v41, v62
	v_add_f32_e32 v46, v46, v63
	v_add_f32_e32 v47, v47, v64
	v_add_f32_e32 v57, v57, v65
	s_waitcnt lgkmcnt(0)
	v_lshlrev_b32_e32 v62, 16, v42
	v_and_b32_e32 v42, 0xffff0000, v42
	v_lshlrev_b32_e32 v63, 16, v43
	v_and_b32_e32 v43, 0xffff0000, v43
	v_lshlrev_b32_e32 v64, 16, v44
	v_and_b32_e32 v44, 0xffff0000, v44
	v_lshlrev_b32_e32 v65, 16, v45
	v_and_b32_e32 v45, 0xffff0000, v45
	v_add_f32_e32 v58, v58, v42
	v_add_f32_e32 v59, v59, v43
	v_add_f32_e32 v60, v60, v44
	v_add_f32_e32 v61, v61, v45
	ds_read_b128 v[42:45], v149 offset:4016
	v_add_f32_e32 v41, v41, v62
	v_add_f32_e32 v46, v46, v63
	v_add_f32_e32 v47, v47, v64
	v_add_f32_e32 v57, v57, v65
	s_waitcnt lgkmcnt(0)
	v_lshlrev_b32_e32 v62, 16, v42
	v_and_b32_e32 v42, 0xffff0000, v42
	v_lshlrev_b32_e32 v63, 16, v43
	v_and_b32_e32 v43, 0xffff0000, v43
	v_lshlrev_b32_e32 v64, 16, v44
	v_and_b32_e32 v44, 0xffff0000, v44
	v_lshlrev_b32_e32 v65, 16, v45
	v_and_b32_e32 v45, 0xffff0000, v45
	v_add_f32_e32 v66, v58, v42
	v_add_f32_e32 v67, v59, v43
	v_add_f32_e32 v68, v60, v44
	v_add_f32_e32 v69, v61, v45
	ds_read_b128 v[58:61], v149 offset:4544
	v_add_f32_e32 v62, v41, v62
	v_add_f32_e32 v63, v46, v63
	v_add_f32_e32 v64, v47, v64
	v_add_f32_e32 v65, v57, v65
	s_waitcnt lgkmcnt(0)
	v_lshlrev_b32_e32 v41, 16, v58
	v_and_b32_e32 v42, 0xffff0000, v58
	v_lshlrev_b32_e32 v43, 16, v59
	v_and_b32_e32 v44, 0xffff0000, v59
	v_lshlrev_b32_e32 v45, 16, v60
	v_and_b32_e32 v46, 0xffff0000, v60
	v_lshlrev_b32_e32 v47, 16, v61
	v_and_b32_e32 v57, 0xffff0000, v61
	ds_read_b128 v[58:61], v149 offset:5072
	v_add_f32_e32 v66, v66, v42
	v_add_f32_e32 v67, v67, v44
	v_add_f32_e32 v68, v68, v46
	v_add_f32_e32 v69, v69, v57
	s_waitcnt lgkmcnt(0)
	v_lshlrev_b32_e32 v70, 16, v58
	v_and_b32_e32 v58, 0xffff0000, v58
	v_lshlrev_b32_e32 v71, 16, v59
	v_and_b32_e32 v59, 0xffff0000, v59
	v_lshlrev_b32_e32 v131, 16, v60
	v_and_b32_e32 v60, 0xffff0000, v60
	v_lshlrev_b32_e32 v133, 16, v61
	v_and_b32_e32 v61, 0xffff0000, v61
	v_add_f32_e32 v66, v66, v58
	v_add_f32_e32 v67, v67, v59
	v_add_f32_e32 v68, v68, v60
	v_add_f32_e32 v69, v69, v61
	ds_read_b128 v[58:61], v149 offset:5600
	v_add_f32_e32 v62, v62, v41
	v_add_f32_e32 v63, v63, v43
	v_add_f32_e32 v64, v64, v45
	v_add_f32_e32 v65, v65, v47
	v_add_f32_e32 v62, v62, v70
	v_add_f32_e32 v63, v63, v71
	v_add_f32_e32 v64, v64, v131
	v_add_f32_e32 v65, v65, v133
	s_waitcnt lgkmcnt(0)
	v_lshlrev_b32_e32 v70, 16, v58
	v_and_b32_e32 v71, 0xffff0000, v58
	v_lshlrev_b32_e32 v131, 16, v59
	v_and_b32_e32 v133, 0xffff0000, v59
	v_lshlrev_b32_e32 v151, 16, v60
	v_and_b32_e32 v152, 0xffff0000, v60
	v_lshlrev_b32_e32 v153, 16, v61
	v_and_b32_e32 v154, 0xffff0000, v61
	v_add_f32_e32 v58, v62, v70
	v_add_f32_e32 v59, v66, v71
	v_add_f32_e32 v60, v63, v131
	v_add_f32_e32 v61, v67, v133
	v_add_f32_e32 v62, v64, v151
	v_add_f32_e32 v63, v68, v152
	v_add_f32_e32 v64, v65, v153
	v_add_f32_e32 v65, v69, v154
	ds_read_b128 v[66:69], v149 offset:6128
	s_waitcnt lgkmcnt(0)
	v_lshlrev_b32_e32 v70, 16, v66
	v_and_b32_e32 v66, 0xffff0000, v66
	v_lshlrev_b32_e32 v71, 16, v67
	v_and_b32_e32 v67, 0xffff0000, v67
	v_lshlrev_b32_e32 v131, 16, v68
	v_and_b32_e32 v68, 0xffff0000, v68
	v_lshlrev_b32_e32 v133, 16, v69
	v_and_b32_e32 v69, 0xffff0000, v69
	v_add_f32_e32 v58, v58, v70
	v_add_f32_e32 v59, v59, v66
	v_add_f32_e32 v60, v60, v71
	v_add_f32_e32 v61, v61, v67
	v_add_f32_e32 v62, v62, v131
	v_add_f32_e32 v63, v63, v68
	v_add_f32_e32 v64, v64, v133
	v_add_f32_e32 v65, v65, v69
	v_fma_f32 v41, v40, v58, -v41
	v_fma_f32 v42, v40, v59, -v42
	v_fma_f32 v43, v40, v60, -v43
	v_fma_f32 v44, v40, v61, -v44
	v_fma_f32 v45, v40, v62, -v45
	v_fma_f32 v46, v40, v63, -v46
	v_fma_f32 v47, v40, v64, -v47
	v_fma_f32 v40, v40, v65, -v57
	v_cvt_pk_bf16_f32 v58, v41, v42
	v_cvt_pk_bf16_f32 v59, v43, v44
	v_cvt_pk_bf16_f32 v60, v45, v46
	v_cvt_pk_bf16_f32 v61, v47, v40
	s_waitcnt vmcnt(0)
	v_mfma_f32_16x16x32_bf16 v[44:47], v[198:201], v[58:61], v[32:35]
	s_nop 2
	s_waitcnt vmcnt(0)
	v_mfma_f32_16x16x32_bf16 v[40:43], v[202:205], v[58:61], v[36:39]
	s_waitcnt vmcnt(0)
	v_mfma_f32_16x16x32_bf16 v[36:39], v[214:217], v[58:61], v[48:51]
	s_nop 1
	v_max_i32_e32 v48, 8, v56
	v_min_i32_e32 v49, 0x1ff8, v56
	v_sub_u32_e32 v48, v49, v48
	v_add_u32_e32 v48, 16, v48
	v_cvt_f32_i32_e32 v48, v48
	s_waitcnt vmcnt(0)
	v_mfma_f32_16x16x32_bf16 v[32:35], v[218:221], v[58:61], v[52:55]
	v_div_scale_f32 v49, s[18:19], v48, v48, 1.0
	v_rcp_f32_e32 v50, v49
	s_mov_b64 s[18:19], 0x1a000200
	v_fma_f32 v51, -v49, v50, 1.0
	v_fmac_f32_e32 v50, v51, v50
	v_div_scale_f32 v51, vcc, 1.0, v48, 1.0
	v_mul_f32_e32 v52, v51, v50
	v_fma_f32 v53, -v49, v52, v51
	v_fmac_f32_e32 v52, v53, v50
	v_fma_f32 v49, -v49, v52, v51
	v_div_fmas_f32 v49, v49, v50, v52
	v_div_fixup_f32 v56, v49, v48, 1.0
	ds_read_b128 v[48:51], v149 offset:384
	s_waitcnt lgkmcnt(0)
	v_lshlrev_b32_e32 v52, 16, v48
	v_and_b32_e32 v48, 0xffff0000, v48
	v_lshlrev_b32_e32 v53, 16, v49
	v_and_b32_e32 v49, 0xffff0000, v49
	v_lshlrev_b32_e32 v54, 16, v50
	v_and_b32_e32 v50, 0xffff0000, v50
	v_lshlrev_b32_e32 v55, 16, v51
	v_and_b32_e32 v51, 0xffff0000, v51
	v_add_f32_e32 v57, 0, v48
	v_add_f32_e32 v58, 0, v49
	v_add_f32_e32 v59, 0, v50
	v_add_f32_e32 v60, 0, v51
	ds_read_b128 v[48:51], v149 offset:912
	v_add_f32_e32 v52, 0, v52
	v_add_f32_e32 v53, 0, v53
	v_add_f32_e32 v54, 0, v54
	v_add_f32_e32 v55, 0, v55
	s_waitcnt lgkmcnt(0)
	v_lshlrev_b32_e32 v61, 16, v48
	v_and_b32_e32 v48, 0xffff0000, v48
	v_lshlrev_b32_e32 v62, 16, v49
	v_and_b32_e32 v49, 0xffff0000, v49
	v_lshlrev_b32_e32 v63, 16, v50
	v_and_b32_e32 v50, 0xffff0000, v50
	v_lshlrev_b32_e32 v64, 16, v51
	v_and_b32_e32 v51, 0xffff0000, v51
	v_add_f32_e32 v57, v57, v48
	v_add_f32_e32 v58, v58, v49
	v_add_f32_e32 v59, v59, v50
	v_add_f32_e32 v60, v60, v51
	ds_read_b128 v[48:51], v149 offset:1440
	v_add_f32_e32 v52, v52, v61
	v_add_f32_e32 v53, v53, v62
	v_add_f32_e32 v54, v54, v63
	v_add_f32_e32 v55, v55, v64
	s_waitcnt lgkmcnt(0)
	v_lshlrev_b32_e32 v61, 16, v48
	v_and_b32_e32 v48, 0xffff0000, v48
	v_lshlrev_b32_e32 v62, 16, v49
	v_and_b32_e32 v49, 0xffff0000, v49
	v_lshlrev_b32_e32 v63, 16, v50
	v_and_b32_e32 v50, 0xffff0000, v50
	v_lshlrev_b32_e32 v64, 16, v51
	v_and_b32_e32 v51, 0xffff0000, v51
	v_add_f32_e32 v57, v57, v48
	v_add_f32_e32 v58, v58, v49
	v_add_f32_e32 v59, v59, v50
	v_add_f32_e32 v60, v60, v51
	ds_read_b128 v[48:51], v149 offset:1968
	v_add_f32_e32 v52, v52, v61
	v_add_f32_e32 v53, v53, v62
	v_add_f32_e32 v54, v54, v63
	v_add_f32_e32 v55, v55, v64
	s_waitcnt lgkmcnt(0)
	v_lshlrev_b32_e32 v61, 16, v48
	v_and_b32_e32 v48, 0xffff0000, v48
	v_lshlrev_b32_e32 v62, 16, v49
	v_and_b32_e32 v49, 0xffff0000, v49
	v_lshlrev_b32_e32 v63, 16, v50
	v_and_b32_e32 v50, 0xffff0000, v50
	v_lshlrev_b32_e32 v64, 16, v51
	v_and_b32_e32 v51, 0xffff0000, v51
	v_add_f32_e32 v57, v57, v48
	v_add_f32_e32 v58, v58, v49
	v_add_f32_e32 v59, v59, v50
	v_add_f32_e32 v60, v60, v51
	ds_read_b128 v[48:51], v149 offset:2496
	v_add_f32_e32 v52, v52, v61
	v_add_f32_e32 v53, v53, v62
	v_add_f32_e32 v54, v54, v63
	v_add_f32_e32 v55, v55, v64
	s_waitcnt lgkmcnt(0)
	v_lshlrev_b32_e32 v61, 16, v48
	v_and_b32_e32 v48, 0xffff0000, v48
	v_lshlrev_b32_e32 v62, 16, v49
	v_and_b32_e32 v49, 0xffff0000, v49
	v_lshlrev_b32_e32 v63, 16, v50
	v_and_b32_e32 v50, 0xffff0000, v50
	v_lshlrev_b32_e32 v64, 16, v51
	v_and_b32_e32 v51, 0xffff0000, v51
	v_add_f32_e32 v57, v57, v48
	v_add_f32_e32 v58, v58, v49
	v_add_f32_e32 v59, v59, v50
	v_add_f32_e32 v60, v60, v51
	ds_read_b128 v[48:51], v149 offset:3024
	v_add_f32_e32 v52, v52, v61
	v_add_f32_e32 v53, v53, v62
	v_add_f32_e32 v54, v54, v63
	v_add_f32_e32 v55, v55, v64
	s_waitcnt lgkmcnt(0)
	v_lshlrev_b32_e32 v61, 16, v48
	v_and_b32_e32 v48, 0xffff0000, v48
	v_lshlrev_b32_e32 v62, 16, v49
	v_and_b32_e32 v49, 0xffff0000, v49
	v_lshlrev_b32_e32 v63, 16, v50
	v_and_b32_e32 v50, 0xffff0000, v50
	v_lshlrev_b32_e32 v64, 16, v51
	v_and_b32_e32 v51, 0xffff0000, v51
	v_add_f32_e32 v57, v57, v48
	v_add_f32_e32 v58, v58, v49
	v_add_f32_e32 v59, v59, v50
	v_add_f32_e32 v60, v60, v51
	ds_read_b128 v[48:51], v149 offset:3552
	v_add_f32_e32 v52, v52, v61
	v_add_f32_e32 v53, v53, v62
	v_add_f32_e32 v54, v54, v63
	v_add_f32_e32 v55, v55, v64
	s_waitcnt lgkmcnt(0)
	v_lshlrev_b32_e32 v61, 16, v48
	v_and_b32_e32 v48, 0xffff0000, v48
	v_lshlrev_b32_e32 v62, 16, v49
	v_and_b32_e32 v49, 0xffff0000, v49
	v_lshlrev_b32_e32 v63, 16, v50
	v_and_b32_e32 v50, 0xffff0000, v50
	v_lshlrev_b32_e32 v64, 16, v51
	v_and_b32_e32 v51, 0xffff0000, v51
	v_add_f32_e32 v57, v57, v48
	v_add_f32_e32 v58, v58, v49
	v_add_f32_e32 v59, v59, v50
	v_add_f32_e32 v60, v60, v51
	ds_read_b128 v[48:51], v149 offset:4080
	v_add_f32_e32 v52, v52, v61
	v_add_f32_e32 v53, v53, v62
	v_add_f32_e32 v54, v54, v63
	v_add_f32_e32 v55, v55, v64
	s_waitcnt lgkmcnt(0)
	v_lshlrev_b32_e32 v61, 16, v48
	v_lshlrev_b32_e32 v62, 16, v49
	v_lshlrev_b32_e32 v63, 16, v50
	v_lshlrev_b32_e32 v64, 16, v51
	v_add_f32_e32 v61, v52, v61
	v_add_f32_e32 v62, v53, v62
	v_add_f32_e32 v63, v54, v63
	v_add_f32_e32 v64, v55, v64
	ds_read_b128 v[52:55], v149 offset:4608
	v_and_b32_e32 v48, 0xffff0000, v48
	v_and_b32_e32 v49, 0xffff0000, v49
	v_and_b32_e32 v50, 0xffff0000, v50
	v_and_b32_e32 v51, 0xffff0000, v51
	v_add_f32_e32 v57, v57, v48
	v_add_f32_e32 v58, v58, v49
	v_add_f32_e32 v59, v59, v50
	v_add_f32_e32 v60, v60, v51
	s_waitcnt lgkmcnt(0)
	v_lshlrev_b32_e32 v48, 16, v52
	v_and_b32_e32 v49, 0xffff0000, v52
	v_lshlrev_b32_e32 v50, 16, v53
	v_and_b32_e32 v51, 0xffff0000, v53
	v_lshlrev_b32_e32 v52, 16, v54
	v_and_b32_e32 v53, 0xffff0000, v54
	v_lshlrev_b32_e32 v54, 16, v55
	v_and_b32_e32 v55, 0xffff0000, v55
	v_add_f32_e32 v65, v61, v48
	v_add_f32_e32 v66, v58, v51
	v_add_f32_e32 v67, v59, v53
	v_add_f32_e32 v68, v60, v55
	ds_read_b128 v[58:61], v149 offset:5136
	v_add_f32_e32 v57, v57, v49
	v_add_f32_e32 v62, v62, v50
	v_add_f32_e32 v63, v63, v52
	v_add_f32_e32 v64, v64, v54
	s_waitcnt lgkmcnt(0)
	v_lshlrev_b32_e32 v69, 16, v58
	v_and_b32_e32 v58, 0xffff0000, v58
	v_lshlrev_b32_e32 v70, 16, v59
	v_and_b32_e32 v59, 0xffff0000, v59
	v_lshlrev_b32_e32 v71, 16, v60
	v_and_b32_e32 v60, 0xffff0000, v60
	v_lshlrev_b32_e32 v131, 16, v61
	v_and_b32_e32 v61, 0xffff0000, v61
	v_add_f32_e32 v57, v57, v58
	v_add_f32_e32 v66, v66, v59
	v_add_f32_e32 v67, v67, v60
	v_add_f32_e32 v68, v68, v61
	ds_read_b128 v[58:61], v149 offset:5664
	v_add_f32_e32 v65, v65, v69
	v_add_f32_e32 v62, v62, v70
	v_add_f32_e32 v63, v63, v71
	v_add_f32_e32 v64, v64, v131
	s_waitcnt lgkmcnt(0)
	v_lshlrev_b32_e32 v69, 16, v58
	v_and_b32_e32 v58, 0xffff0000, v58
	v_lshlrev_b32_e32 v70, 16, v59
	v_and_b32_e32 v59, 0xffff0000, v59
	v_lshlrev_b32_e32 v71, 16, v60
	v_and_b32_e32 v60, 0xffff0000, v60
	v_lshlrev_b32_e32 v131, 16, v61
	v_and_b32_e32 v61, 0xffff0000, v61
	v_add_f32_e32 v57, v57, v58
	v_add_f32_e32 v66, v66, v59
	v_add_f32_e32 v67, v67, v60
	v_add_f32_e32 v68, v68, v61
	ds_read_b128 v[58:61], v149 offset:6192
	v_add_f32_e32 v65, v65, v69
	v_add_f32_e32 v62, v62, v70
	v_add_f32_e32 v63, v63, v71
	v_add_f32_e32 v64, v64, v131
	s_waitcnt lgkmcnt(0)
	v_lshlrev_b32_e32 v69, 16, v58
	v_and_b32_e32 v58, 0xffff0000, v58
	v_lshlrev_b32_e32 v70, 16, v59
	v_and_b32_e32 v59, 0xffff0000, v59
	v_lshlrev_b32_e32 v71, 16, v60
	v_and_b32_e32 v60, 0xffff0000, v60
	v_lshlrev_b32_e32 v131, 16, v61
	v_and_b32_e32 v61, 0xffff0000, v61
	v_add_f32_e32 v57, v57, v58
	v_add_f32_e32 v66, v66, v59
	v_add_f32_e32 v67, v67, v60
	v_add_f32_e32 v68, v68, v61
	ds_read_b128 v[58:61], v149 offset:6720
	v_add_f32_e32 v65, v65, v69
	v_add_f32_e32 v62, v62, v70
	v_add_f32_e32 v63, v63, v71
	v_add_f32_e32 v64, v64, v131
	s_waitcnt lgkmcnt(0)
	v_lshlrev_b32_e32 v69, 16, v58
	v_and_b32_e32 v58, 0xffff0000, v58
	v_lshlrev_b32_e32 v70, 16, v59
	v_and_b32_e32 v59, 0xffff0000, v59
	v_lshlrev_b32_e32 v71, 16, v60
	v_and_b32_e32 v60, 0xffff0000, v60
	v_lshlrev_b32_e32 v131, 16, v61
	v_and_b32_e32 v61, 0xffff0000, v61
	v_add_f32_e32 v57, v57, v58
	v_add_f32_e32 v66, v66, v59
	v_add_f32_e32 v67, v67, v60
	v_add_f32_e32 v68, v68, v61
	ds_read_b128 v[58:61], v149 offset:7248
	v_add_f32_e32 v65, v65, v69
	v_add_f32_e32 v62, v62, v70
	v_add_f32_e32 v63, v63, v71
	v_add_f32_e32 v64, v64, v131
	s_waitcnt lgkmcnt(0)
	v_lshlrev_b32_e32 v69, 16, v58
	v_and_b32_e32 v58, 0xffff0000, v58
	v_lshlrev_b32_e32 v70, 16, v59
	v_and_b32_e32 v59, 0xffff0000, v59
	v_lshlrev_b32_e32 v71, 16, v60
	v_and_b32_e32 v60, 0xffff0000, v60
	v_lshlrev_b32_e32 v131, 16, v61
	v_and_b32_e32 v61, 0xffff0000, v61
	v_add_f32_e32 v65, v65, v69
	v_add_f32_e32 v69, v57, v58
	v_add_f32_e32 v66, v66, v59
	v_add_f32_e32 v67, v67, v60
	v_add_f32_e32 v68, v68, v61
	ds_read_b128 v[58:61], v149 offset:7776
	v_add_f32_e32 v63, v63, v71
	v_add_f32_e32 v64, v64, v131
	v_add_f32_e32 v62, v62, v70
	s_waitcnt lgkmcnt(0)
	v_lshlrev_b32_e32 v131, 16, v60
	v_lshlrev_b32_e32 v151, 16, v61
	v_and_b32_e32 v152, 0xffff0000, v61
	v_add_f32_e32 v61, v63, v131
	v_add_f32_e32 v63, v64, v151
	v_add_f32_e32 v64, v68, v152
	ds_read_b128 v[152:155], v149 offset:8304
	v_lshlrev_b32_e32 v57, 16, v58
	v_and_b32_e32 v58, 0xffff0000, v58
	v_lshlrev_b32_e32 v70, 16, v59
	v_and_b32_e32 v71, 0xffff0000, v59
	v_and_b32_e32 v133, 0xffff0000, v60
	v_add_f32_e32 v57, v65, v57
	v_add_f32_e32 v58, v69, v58
	v_add_f32_e32 v59, v62, v70
	v_add_f32_e32 v60, v66, v71
	v_add_f32_e32 v62, v67, v133
	s_waitcnt lgkmcnt(0)
	v_lshlrev_b32_e32 v65, 16, v152
	v_and_b32_e32 v66, 0xffff0000, v152
	v_lshlrev_b32_e32 v67, 16, v153
	v_and_b32_e32 v68, 0xffff0000, v153
	v_lshlrev_b32_e32 v69, 16, v154
	v_and_b32_e32 v70, 0xffff0000, v154
	v_lshlrev_b32_e32 v71, 16, v155
	v_and_b32_e32 v131, 0xffff0000, v155
	v_add_f32_e32 v57, v57, v65
	v_add_f32_e32 v58, v58, v66
	v_add_f32_e32 v59, v59, v67
	v_add_f32_e32 v60, v60, v68
	v_add_f32_e32 v61, v61, v69
	v_add_f32_e32 v62, v62, v70
	v_add_f32_e32 v63, v63, v71
	v_add_f32_e32 v64, v64, v131
	v_fma_f32 v48, v56, v57, -v48
	v_fma_f32 v49, v56, v58, -v49
	v_fma_f32 v50, v56, v59, -v50
	v_fma_f32 v51, v56, v60, -v51
	v_fma_f32 v52, v56, v61, -v52
	v_fma_f32 v53, v56, v62, -v53
	v_fma_f32 v54, v56, v63, -v54
	v_fma_f32 v55, v56, v64, -v55
	v_cvt_pk_bf16_f32 v58, v48, v49
	v_cvt_pk_bf16_f32 v59, v50, v51
	v_cvt_pk_bf16_f32 v60, v52, v53
	v_cvt_pk_bf16_f32 v61, v54, v55
	s_waitcnt vmcnt(3)
	v_mfma_f32_16x16x32_bf16 v[48:51], v[90:93], v[58:61], 0
	s_waitcnt vmcnt(2)
	v_mfma_f32_16x16x32_bf16 v[52:55], v[94:97], v[58:61], 0
	s_waitcnt vmcnt(1)
	v_mfma_f32_16x16x32_bf16 v[64:67], v[106:109], v[58:61], 0
	s_waitcnt vmcnt(0)
	v_mfma_f32_16x16x32_bf16 v[68:71], v[110:113], v[58:61], 0
	ds_read_b128 v[58:61], v149 offset:448
	s_waitcnt lgkmcnt(0)
	v_lshlrev_b32_e32 v57, 16, v58
	v_and_b32_e32 v58, 0xffff0000, v58
	v_lshlrev_b32_e32 v62, 16, v59
	v_and_b32_e32 v59, 0xffff0000, v59
	v_lshlrev_b32_e32 v63, 16, v60
	v_and_b32_e32 v60, 0xffff0000, v60
	v_lshlrev_b32_e32 v131, 16, v61
	v_and_b32_e32 v61, 0xffff0000, v61
	v_add_f32_e32 v133, 0, v58
	v_add_f32_e32 v151, 0, v59
	v_add_f32_e32 v152, 0, v60
	v_add_f32_e32 v153, 0, v61
	ds_read_b128 v[58:61], v149 offset:976
	v_add_f32_e32 v57, 0, v57
	v_add_f32_e32 v62, 0, v62
	v_add_f32_e32 v63, 0, v63
	v_add_f32_e32 v131, 0, v131
	s_waitcnt lgkmcnt(0)
	v_lshlrev_b32_e32 v154, 16, v58
	v_and_b32_e32 v58, 0xffff0000, v58
	v_lshlrev_b32_e32 v155, 16, v59
	v_and_b32_e32 v59, 0xffff0000, v59
	v_lshlrev_b32_e32 v156, 16, v60
	v_and_b32_e32 v60, 0xffff0000, v60
	v_lshlrev_b32_e32 v157, 16, v61
	v_and_b32_e32 v61, 0xffff0000, v61
	v_add_f32_e32 v133, v133, v58
	v_add_f32_e32 v151, v151, v59
	v_add_f32_e32 v152, v152, v60
	v_add_f32_e32 v153, v153, v61
	ds_read_b128 v[58:61], v149 offset:1504
	v_add_f32_e32 v57, v57, v154
	v_add_f32_e32 v62, v62, v155
	v_add_f32_e32 v63, v63, v156
	v_add_f32_e32 v131, v131, v157
	s_waitcnt lgkmcnt(0)
	v_lshlrev_b32_e32 v154, 16, v58
	v_and_b32_e32 v58, 0xffff0000, v58
	v_lshlrev_b32_e32 v155, 16, v59
	v_and_b32_e32 v59, 0xffff0000, v59
	v_lshlrev_b32_e32 v156, 16, v60
	v_and_b32_e32 v60, 0xffff0000, v60
	v_lshlrev_b32_e32 v157, 16, v61
	v_and_b32_e32 v61, 0xffff0000, v61
	v_add_f32_e32 v133, v133, v58
	v_add_f32_e32 v151, v151, v59
	v_add_f32_e32 v152, v152, v60
	v_add_f32_e32 v153, v153, v61
	ds_read_b128 v[58:61], v149 offset:2032
	v_add_f32_e32 v57, v57, v154
	v_add_f32_e32 v62, v62, v155
	v_add_f32_e32 v63, v63, v156
	v_add_f32_e32 v131, v131, v157
	s_waitcnt lgkmcnt(0)
	v_lshlrev_b32_e32 v154, 16, v58
	v_and_b32_e32 v58, 0xffff0000, v58
	v_lshlrev_b32_e32 v155, 16, v59
	v_and_b32_e32 v59, 0xffff0000, v59
	v_lshlrev_b32_e32 v156, 16, v60
	v_and_b32_e32 v60, 0xffff0000, v60
	v_lshlrev_b32_e32 v157, 16, v61
	v_and_b32_e32 v61, 0xffff0000, v61
	v_add_f32_e32 v133, v133, v58
	v_add_f32_e32 v151, v151, v59
	v_add_f32_e32 v152, v152, v60
	v_add_f32_e32 v153, v153, v61
	ds_read_b128 v[58:61], v149 offset:2560
	v_add_f32_e32 v57, v57, v154
	v_add_f32_e32 v62, v62, v155
	v_add_f32_e32 v63, v63, v156
	v_add_f32_e32 v131, v131, v157
	s_waitcnt lgkmcnt(0)
	v_lshlrev_b32_e32 v154, 16, v58
	v_and_b32_e32 v58, 0xffff0000, v58
	v_lshlrev_b32_e32 v155, 16, v59
	v_and_b32_e32 v59, 0xffff0000, v59
	v_lshlrev_b32_e32 v156, 16, v60
	v_and_b32_e32 v60, 0xffff0000, v60
	v_lshlrev_b32_e32 v157, 16, v61
	v_and_b32_e32 v61, 0xffff0000, v61
	v_add_f32_e32 v133, v133, v58
	v_add_f32_e32 v151, v151, v59
	v_add_f32_e32 v152, v152, v60
	v_add_f32_e32 v153, v153, v61
	ds_read_b128 v[58:61], v149 offset:3088
	v_add_f32_e32 v57, v57, v154
	v_add_f32_e32 v62, v62, v155
	v_add_f32_e32 v63, v63, v156
	v_add_f32_e32 v131, v131, v157
	s_waitcnt lgkmcnt(0)
	v_lshlrev_b32_e32 v154, 16, v58
	v_and_b32_e32 v58, 0xffff0000, v58
	v_lshlrev_b32_e32 v155, 16, v59
	v_and_b32_e32 v59, 0xffff0000, v59
	v_lshlrev_b32_e32 v156, 16, v60
	v_and_b32_e32 v60, 0xffff0000, v60
	v_lshlrev_b32_e32 v157, 16, v61
	v_and_b32_e32 v61, 0xffff0000, v61
	v_add_f32_e32 v133, v133, v58
	v_add_f32_e32 v151, v151, v59
	v_add_f32_e32 v152, v152, v60
	v_add_f32_e32 v153, v153, v61
	ds_read_b128 v[58:61], v149 offset:3616
	v_add_f32_e32 v57, v57, v154
	v_add_f32_e32 v62, v62, v155
	v_add_f32_e32 v63, v63, v156
	v_add_f32_e32 v131, v131, v157
	s_waitcnt lgkmcnt(0)
	v_lshlrev_b32_e32 v154, 16, v58
	v_and_b32_e32 v58, 0xffff0000, v58
	v_lshlrev_b32_e32 v155, 16, v59
	v_and_b32_e32 v59, 0xffff0000, v59
	v_lshlrev_b32_e32 v156, 16, v60
	v_and_b32_e32 v60, 0xffff0000, v60
	v_lshlrev_b32_e32 v157, 16, v61
	v_and_b32_e32 v61, 0xffff0000, v61
	v_add_f32_e32 v133, v133, v58
	v_add_f32_e32 v151, v151, v59
	v_add_f32_e32 v152, v152, v60
	v_add_f32_e32 v153, v153, v61
	ds_read_b128 v[58:61], v149 offset:4144
	v_add_f32_e32 v57, v57, v154
	v_add_f32_e32 v62, v62, v155
	v_add_f32_e32 v63, v63, v156
	v_add_f32_e32 v131, v131, v157
	s_waitcnt lgkmcnt(0)
	v_lshlrev_b32_e32 v154, 16, v58
	v_lshlrev_b32_e32 v155, 16, v59
	v_lshlrev_b32_e32 v156, 16, v60
	v_and_b32_e32 v60, 0xffff0000, v60
	v_lshlrev_b32_e32 v157, 16, v61
	v_and_b32_e32 v61, 0xffff0000, v61
	v_add_f32_e32 v158, v57, v154
	v_add_f32_e32 v159, v62, v155
	v_add_f32_e32 v160, v152, v60
	v_add_f32_e32 v161, v153, v61
	ds_read_b128 v[152:155], v149 offset:4672
	v_and_b32_e32 v58, 0xffff0000, v58
	v_and_b32_e32 v59, 0xffff0000, v59
	v_add_f32_e32 v133, v133, v58
	v_add_f32_e32 v151, v151, v59
	v_add_f32_e32 v156, v63, v156
	v_add_f32_e32 v157, v131, v157
	s_waitcnt lgkmcnt(0)
	v_lshlrev_b32_e32 v57, 16, v152
	v_and_b32_e32 v58, 0xffff0000, v152
	v_lshlrev_b32_e32 v59, 16, v153
	v_and_b32_e32 v60, 0xffff0000, v153
	v_lshlrev_b32_e32 v61, 16, v154
	v_and_b32_e32 v62, 0xffff0000, v154
	v_lshlrev_b32_e32 v63, 16, v155
	v_and_b32_e32 v131, 0xffff0000, v155
	ds_read_b128 v[152:155], v149 offset:5200
	v_add_f32_e32 v133, v133, v58
	v_add_f32_e32 v151, v151, v60
	v_add_f32_e32 v160, v160, v62
	v_add_f32_e32 v161, v161, v131
	s_waitcnt lgkmcnt(0)
	v_lshlrev_b32_e32 v162, 16, v152
	v_and_b32_e32 v152, 0xffff0000, v152
	v_lshlrev_b32_e32 v163, 16, v153
	v_and_b32_e32 v153, 0xffff0000, v153
	v_lshlrev_b32_e32 v164, 16, v154
	v_and_b32_e32 v154, 0xffff0000, v154
	v_lshlrev_b32_e32 v165, 16, v155
	v_and_b32_e32 v155, 0xffff0000, v155
	v_add_f32_e32 v133, v133, v152
	v_add_f32_e32 v151, v151, v153
	v_add_f32_e32 v160, v160, v154
	v_add_f32_e32 v161, v161, v155
	ds_read_b128 v[152:155], v149 offset:5728
	v_add_f32_e32 v158, v158, v57
	v_add_f32_e32 v159, v159, v59
	v_add_f32_e32 v156, v156, v61
	v_add_f32_e32 v157, v157, v63
	v_add_f32_e32 v158, v158, v162
	v_add_f32_e32 v159, v159, v163
	v_add_f32_e32 v156, v156, v164
	v_add_f32_e32 v157, v157, v165
	s_waitcnt lgkmcnt(0)
	v_lshlrev_b32_e32 v162, 16, v152
	v_and_b32_e32 v152, 0xffff0000, v152
	v_lshlrev_b32_e32 v163, 16, v153
	v_and_b32_e32 v153, 0xffff0000, v153
	v_lshlrev_b32_e32 v164, 16, v154
	v_and_b32_e32 v154, 0xffff0000, v154
	v_lshlrev_b32_e32 v165, 16, v155
	v_and_b32_e32 v155, 0xffff0000, v155
	v_add_f32_e32 v133, v133, v152
	v_add_f32_e32 v151, v151, v153
	v_add_f32_e32 v160, v160, v154
	v_add_f32_e32 v161, v161, v155
	ds_read_b128 v[152:155], v149 offset:6256
	v_add_f32_e32 v158, v158, v162
	v_add_f32_e32 v159, v159, v163
	v_add_f32_e32 v156, v156, v164
	v_add_f32_e32 v157, v157, v165
	s_waitcnt lgkmcnt(0)
	v_lshlrev_b32_e32 v162, 16, v152
	v_and_b32_e32 v152, 0xffff0000, v152
	v_lshlrev_b32_e32 v163, 16, v153
	v_and_b32_e32 v153, 0xffff0000, v153
	v_lshlrev_b32_e32 v164, 16, v154
	v_and_b32_e32 v154, 0xffff0000, v154
	v_lshlrev_b32_e32 v165, 16, v155
	v_and_b32_e32 v155, 0xffff0000, v155
	v_add_f32_e32 v133, v133, v152
	v_add_f32_e32 v151, v151, v153
	v_add_f32_e32 v160, v160, v154
	v_add_f32_e32 v161, v161, v155
	ds_read_b128 v[152:155], v149 offset:6784
	v_add_f32_e32 v158, v158, v162
	v_add_f32_e32 v159, v159, v163
	v_add_f32_e32 v156, v156, v164
	v_add_f32_e32 v157, v157, v165
	s_waitcnt lgkmcnt(0)
	v_lshlrev_b32_e32 v162, 16, v152
	v_and_b32_e32 v152, 0xffff0000, v152
	v_lshlrev_b32_e32 v163, 16, v153
	v_and_b32_e32 v153, 0xffff0000, v153
	v_lshlrev_b32_e32 v164, 16, v154
	v_and_b32_e32 v154, 0xffff0000, v154
	v_lshlrev_b32_e32 v165, 16, v155
	v_and_b32_e32 v155, 0xffff0000, v155
	v_add_f32_e32 v133, v133, v152
	v_add_f32_e32 v151, v151, v153
	v_add_f32_e32 v160, v160, v154
	v_add_f32_e32 v161, v161, v155
	ds_read_b128 v[152:155], v149 offset:7312
	v_add_f32_e32 v158, v158, v162
	v_add_f32_e32 v159, v159, v163
	v_add_f32_e32 v156, v156, v164
	v_add_f32_e32 v157, v157, v165
	s_waitcnt lgkmcnt(0)
	v_lshlrev_b32_e32 v162, 16, v152
	v_and_b32_e32 v152, 0xffff0000, v152
	v_lshlrev_b32_e32 v163, 16, v153
	v_and_b32_e32 v153, 0xffff0000, v153
	v_lshlrev_b32_e32 v164, 16, v154
	v_and_b32_e32 v154, 0xffff0000, v154
	v_lshlrev_b32_e32 v165, 16, v155
	v_and_b32_e32 v155, 0xffff0000, v155
	v_add_f32_e32 v133, v133, v152
	v_add_f32_e32 v151, v151, v153
	v_add_f32_e32 v160, v160, v154
	v_add_f32_e32 v161, v161, v155
	ds_read_b128 v[152:155], v149 offset:7840
	v_add_f32_e32 v158, v158, v162
	v_add_f32_e32 v159, v159, v163
	v_add_f32_e32 v156, v156, v164
	v_add_f32_e32 v157, v157, v165
	s_waitcnt lgkmcnt(0)
	v_lshlrev_b32_e32 v162, 16, v152
	v_and_b32_e32 v152, 0xffff0000, v152
	v_lshlrev_b32_e32 v163, 16, v153
	v_and_b32_e32 v153, 0xffff0000, v153
	v_lshlrev_b32_e32 v164, 16, v154
	v_and_b32_e32 v154, 0xffff0000, v154
	v_lshlrev_b32_e32 v165, 16, v155
	v_and_b32_e32 v155, 0xffff0000, v155
	v_add_f32_e32 v133, v133, v152
	v_add_f32_e32 v151, v151, v153
	v_add_f32_e32 v160, v160, v154
	v_add_f32_e32 v161, v161, v155
	ds_read_b128 v[152:155], v149 offset:8368
	v_add_f32_e32 v158, v158, v162
	v_add_f32_e32 v159, v159, v163
	v_add_f32_e32 v156, v156, v164
	v_add_f32_e32 v157, v157, v165
	s_waitcnt lgkmcnt(0)
	v_lshlrev_b32_e32 v162, 16, v152
	v_and_b32_e32 v152, 0xffff0000, v152
	v_lshlrev_b32_e32 v163, 16, v153
	v_and_b32_e32 v153, 0xffff0000, v153
	v_lshlrev_b32_e32 v164, 16, v154
	v_and_b32_e32 v154, 0xffff0000, v154
	v_lshlrev_b32_e32 v165, 16, v155
	v_and_b32_e32 v155, 0xffff0000, v155
	v_add_f32_e32 v158, v158, v162
	v_add_f32_e32 v133, v133, v152
	v_add_f32_e32 v152, v159, v163
	v_add_f32_e32 v151, v151, v153
	v_add_f32_e32 v153, v156, v164
	v_add_f32_e32 v154, v160, v154
	v_add_f32_e32 v156, v157, v165
	v_add_f32_e32 v155, v161, v155
	v_fma_f32 v57, v56, v158, -v57
	v_fma_f32 v58, v56, v133, -v58
	v_fma_f32 v59, v56, v152, -v59
	v_fma_f32 v60, v56, v151, -v60
	v_fma_f32 v61, v56, v153, -v61
	v_fma_f32 v62, v56, v154, -v62
	v_fma_f32 v63, v56, v156, -v63
	v_fma_f32 v56, v56, v155, -v131
	v_cvt_pk_bf16_f32 v152, v57, v58
	v_cvt_pk_bf16_f32 v153, v59, v60
	v_cvt_pk_bf16_f32 v154, v61, v62
	v_cvt_pk_bf16_f32 v155, v63, v56
	s_waitcnt vmcnt(0)
	v_mfma_f32_16x16x32_bf16 v[60:63], v[222:225], v[152:155], v[48:51]
	s_nop 2
	v_mov_b32_e32 v133, v209
	s_waitcnt vmcnt(0)
	v_mfma_f32_16x16x32_bf16 v[56:59], v[226:229], v[152:155], v[52:55]
	s_waitcnt vmcnt(0)
	v_mfma_f32_16x16x32_bf16 v[52:55], v[230:233], v[152:155], v[64:67]
	s_nop 1
	v_pk_mul_f32 v[64:65], v[14:15], v[14:15]
	v_pk_mul_f32 v[66:67], v[12:13], v[12:13]
	s_waitcnt vmcnt(0)
	v_mfma_f32_16x16x32_bf16 v[48:51], v[234:237], v[152:155], v[68:71]
	s_nop 2
	v_pk_mov_b32 v[68:69], v[66:67], v[64:65] op_sel:[1,0]
	v_mov_b32_e32 v67, v65
	v_pk_add_f32 v[64:65], v[68:69], v[66:67]
	v_pk_mul_f32 v[66:67], v[10:11], v[10:11]
	v_pk_mul_f32 v[68:69], v[8:9], v[8:9]
	v_pk_add_f32 v[64:65], v[64:65], v[64:65] op_sel:[0,1] op_sel_hi:[1,0]
	v_pk_mov_b32 v[70:71], v[68:69], v[66:67] op_sel:[1,0]
	v_mov_b32_e32 v69, v67
	v_pk_add_f32 v[66:67], v[70:71], v[68:69]
	v_mul_f32_e32 v68, v0, v0
	v_mul_f32_e32 v69, v1, v1
	v_pk_add_f32 v[66:67], v[66:67], v[66:67] op_sel:[0,1] op_sel_hi:[1,0]
	v_mov_b32_e32 v65, v68
	v_mov_b32_e32 v67, v69
	v_pk_add_f32 v[64:65], v[64:65], v[66:67]
	v_mul_f32_e32 v66, v5, v5
	v_mul_f32_e32 v68, v7, v7
	v_mul_f32_e32 v70, v2, v2
	v_mul_f32_e32 v71, v3, v3
	v_pk_fma_f32 v[66:67], v[4:5], v[4:5], v[66:67] op_sel_hi:[1,1,0]
	v_pk_fma_f32 v[68:69], v[6:7], v[6:7], v[68:69] op_sel_hi:[1,1,0]
	v_mov_b32_e32 v67, v70
	v_mov_b32_e32 v69, v71
	v_pk_add_f32 v[66:67], v[66:67], v[68:69]
	v_pk_mul_f32 v[68:69], v[28:29], v[28:29]
	v_pk_add_f32 v[64:65], v[64:65], v[66:67]
	v_pk_mul_f32 v[66:67], v[30:31], v[30:31]
	v_pk_add_f32 v[64:65], v[64:65], v[64:65] op_sel:[0,1] op_sel_hi:[1,0]
	v_pk_mov_b32 v[70:71], v[68:69], v[66:67] op_sel:[1,0]
	v_mov_b32_e32 v69, v67
	v_pk_add_f32 v[66:67], v[70:71], v[68:69]
	v_mul_f32_e32 v68, v20, v20
	v_mul_f32_e32 v69, v21, v21
	v_pk_add_f32 v[66:67], v[66:67], v[66:67] op_sel:[0,1] op_sel_hi:[1,0]
	v_mov_b32_e32 v65, v68
	v_mov_b32_e32 v67, v69
	v_pk_add_f32 v[64:65], v[64:65], v[66:67]
	v_mul_f32_e32 v66, v25, v25
	v_mul_f32_e32 v68, v27, v27
	v_mul_f32_e32 v70, v22, v22
	v_mul_f32_e32 v71, v23, v23
	v_pk_fma_f32 v[66:67], v[24:25], v[24:25], v[66:67] op_sel_hi:[1,1,0]
	v_pk_fma_f32 v[68:69], v[26:27], v[26:27], v[68:69] op_sel_hi:[1,1,0]
	v_mov_b32_e32 v67, v70
	v_mov_b32_e32 v69, v71
	v_pk_add_f32 v[66:67], v[66:67], v[68:69]
	v_pk_mul_f32 v[68:69], v[16:17], v[16:17]
	v_pk_add_f32 v[64:65], v[64:65], v[66:67]
	v_pk_mul_f32 v[66:67], v[18:19], v[18:19]
	v_pk_add_f32 v[64:65], v[64:65], v[64:65] op_sel:[0,1] op_sel_hi:[1,0]
	v_pk_mov_b32 v[70:71], v[68:69], v[66:67] op_sel:[1,0]
	v_mov_b32_e32 v69, v67
	v_pk_add_f32 v[66:67], v[70:71], v[68:69]
	v_mul_f32_e32 v68, v40, v40
	v_mul_f32_e32 v69, v41, v41
	v_pk_add_f32 v[66:67], v[66:67], v[66:67] op_sel:[0,1] op_sel_hi:[1,0]
	v_mov_b32_e32 v65, v68
	v_mov_b32_e32 v67, v69
	v_pk_add_f32 v[64:65], v[64:65], v[66:67]
	v_mul_f32_e32 v66, v45, v45
	v_mul_f32_e32 v68, v47, v47
	v_mul_f32_e32 v70, v42, v42
	v_mul_f32_e32 v71, v43, v43
	v_pk_fma_f32 v[66:67], v[44:45], v[44:45], v[66:67] op_sel_hi:[1,1,0]
	v_pk_fma_f32 v[68:69], v[46:47], v[46:47], v[68:69] op_sel_hi:[1,1,0]
	v_mov_b32_e32 v67, v70
	v_mov_b32_e32 v69, v71
	v_pk_add_f32 v[66:67], v[66:67], v[68:69]
	v_pk_mul_f32 v[68:69], v[36:37], v[36:37]
	v_pk_add_f32 v[64:65], v[64:65], v[66:67]
	v_pk_mul_f32 v[66:67], v[38:39], v[38:39]
	v_pk_add_f32 v[64:65], v[64:65], v[64:65] op_sel:[0,1] op_sel_hi:[1,0]
	v_pk_mov_b32 v[70:71], v[68:69], v[66:67] op_sel:[1,0]
	v_mov_b32_e32 v69, v67
	v_pk_add_f32 v[66:67], v[70:71], v[68:69]
	v_mul_f32_e32 v68, v60, v60
	v_mul_f32_e32 v69, v61, v61
	v_pk_add_f32 v[66:67], v[66:67], v[66:67] op_sel:[0,1] op_sel_hi:[1,0]
	v_mov_b32_e32 v65, v68
	v_mov_b32_e32 v67, v69
	v_pk_add_f32 v[64:65], v[64:65], v[66:67]
	v_mul_f32_e32 v66, v33, v33
	v_mul_f32_e32 v68, v35, v35
	v_mul_f32_e32 v70, v62, v62
	v_mul_f32_e32 v71, v63, v63
	v_pk_fma_f32 v[66:67], v[32:33], v[32:33], v[66:67] op_sel_hi:[1,1,0]
	v_pk_fma_f32 v[68:69], v[34:35], v[34:35], v[68:69] op_sel_hi:[1,1,0]
	v_mov_b32_e32 v67, v70
	v_mov_b32_e32 v69, v71
	v_pk_add_f32 v[66:67], v[66:67], v[68:69]
	v_pk_mul_f32 v[68:69], v[56:57], v[56:57]
	v_pk_add_f32 v[64:65], v[64:65], v[66:67]
	v_pk_mul_f32 v[66:67], v[58:59], v[58:59]
	v_pk_add_f32 v[64:65], v[64:65], v[64:65] op_sel:[0,1] op_sel_hi:[1,0]
	v_pk_mov_b32 v[70:71], v[68:69], v[66:67] op_sel:[1,0]
	v_mov_b32_e32 v69, v67
	v_pk_add_f32 v[66:67], v[70:71], v[68:69]
	v_mul_f32_e32 v68, v48, v48
	v_mul_f32_e32 v69, v49, v49
	v_pk_add_f32 v[66:67], v[66:67], v[66:67] op_sel:[0,1] op_sel_hi:[1,0]
	v_mov_b32_e32 v65, v68
	v_mov_b32_e32 v67, v69
	v_pk_add_f32 v[64:65], v[64:65], v[66:67]
	v_mul_f32_e32 v66, v53, v53
	v_mul_f32_e32 v68, v55, v55
	v_mul_f32_e32 v70, v50, v50
	v_mul_f32_e32 v71, v51, v51
	v_pk_fma_f32 v[66:67], v[52:53], v[52:53], v[66:67] op_sel_hi:[1,1,0]
	v_pk_fma_f32 v[68:69], v[54:55], v[54:55], v[68:69] op_sel_hi:[1,1,0]
	v_mov_b32_e32 v67, v70
	v_mov_b32_e32 v69, v71
	v_pk_add_f32 v[66:67], v[66:67], v[68:69]
	v_and_b32_e32 v68, 64, v245
	v_pk_add_f32 v[64:65], v[64:65], v[66:67]
	v_xor_b32_e32 v67, 16, v245
	v_add_u32_e32 v68, 64, v68
	v_cmp_lt_i32_e32 vcc, v67, v68
	v_add_f32_e32 v66, v64, v65
	v_lshl_add_u64 v[64:65], s[84:85], 0, v[134:135]
	v_cndmask_b32_e32 v67, v245, v67, vcc
	v_lshlrev_b32_e32 v67, 2, v67
	ds_bpermute_b32 v67, v67, v66
	v_lshl_add_u64 v[64:65], v[64:65], 0, v[132:133]
	s_waitcnt lgkmcnt(0)
	v_add_f32_e32 v66, v66, v67
	v_xor_b32_e32 v67, 32, v245
	v_cmp_lt_i32_e32 vcc, v67, v68
	v_lshl_add_u64 v[68:69], v[64:65], 0, s[18:19]
	s_nop 0
	v_cndmask_b32_e32 v67, v245, v67, vcc
	v_lshlrev_b32_e32 v67, 2, v67
	ds_bpermute_b32 v67, v67, v66
	s_waitcnt lgkmcnt(0)
	v_add_f32_e32 v66, v66, v67
	v_fmamk_f32 v66, v66, 0x3b800000, v244
	v_cmp_gt_f32_e32 vcc, s7, v66
	v_mul_f32_e32 v67, 0x4b800000, v66
	s_nop 0
	v_cndmask_b32_e32 v66, v66, v67, vcc
	v_rsq_f32_e32 v66, v66
	s_nop 0
	v_mul_f32_e32 v67, 0x45800000, v66
	v_cndmask_b32_e32 v66, v66, v67, vcc
	v_mul_f32_e32 v12, v12, v66
	v_mul_f32_e32 v13, v13, v66
	v_cvt_pk_bf16_f32 v12, v12, v13
	v_mul_f32_e32 v13, v14, v66
	v_mul_f32_e32 v14, v15, v66
	v_cvt_pk_bf16_f32 v13, v13, v14
	v_add_co_u32_e32 v14, vcc, s47, v64
	v_mul_f32_e32 v8, v8, v66
	s_nop 0
	v_addc_co_u32_e32 v15, vcc, 0, v65, vcc
	v_mul_f32_e32 v9, v9, v66
	global_store_dwordx2 v[14:15], v[12:13], off offset:512
	v_cvt_pk_bf16_f32 v8, v8, v9
	v_mul_f32_e32 v9, v10, v66
	v_mul_f32_e32 v4, v4, v66
	v_mul_f32_e32 v5, v5, v66
	v_mul_f32_e32 v10, v11, v66
	v_cvt_pk_bf16_f32 v9, v9, v10
	global_store_dwordx2 v[68:69], v[8:9], off offset:32
	v_cvt_pk_bf16_f32 v4, v4, v5
	v_mul_f32_e32 v5, v6, v66
	v_mul_f32_e32 v0, v0, v66
	v_mul_f32_e32 v1, v1, v66
	v_mul_f32_e32 v6, v7, v66
	v_cvt_pk_bf16_f32 v5, v5, v6
	global_store_dwordx2 v[68:69], v[4:5], off offset:64
	v_cvt_pk_bf16_f32 v0, v0, v1
	v_mul_f32_e32 v1, v2, v66
	v_mul_f32_e32 v2, v3, v66
	v_cvt_pk_bf16_f32 v1, v1, v2
	global_store_dwordx2 v[68:69], v[0:1], off offset:96
	v_mul_f32_e32 v0, v28, v66
	v_mul_f32_e32 v1, v29, v66
	v_cvt_pk_bf16_f32 v0, v0, v1
	v_mul_f32_e32 v1, v30, v66
	v_mul_f32_e32 v2, v31, v66
	v_cvt_pk_bf16_f32 v1, v1, v2
	global_store_dwordx2 v[68:69], v[0:1], off offset:128
	v_mul_f32_e32 v0, v24, v66
	v_mul_f32_e32 v1, v25, v66
	v_cvt_pk_bf16_f32 v0, v0, v1
	v_mul_f32_e32 v1, v26, v66
	v_mul_f32_e32 v2, v27, v66
	v_cvt_pk_bf16_f32 v1, v1, v2
	global_store_dwordx2 v[68:69], v[0:1], off offset:160
	v_mul_f32_e32 v0, v20, v66
	v_mul_f32_e32 v1, v21, v66
	v_cvt_pk_bf16_f32 v0, v0, v1
	v_mul_f32_e32 v1, v22, v66
	v_mul_f32_e32 v2, v23, v66
	v_cvt_pk_bf16_f32 v1, v1, v2
	global_store_dwordx2 v[68:69], v[0:1], off offset:192
	v_mul_f32_e32 v0, v16, v66
	v_mul_f32_e32 v1, v17, v66
	v_cvt_pk_bf16_f32 v0, v0, v1
	v_mul_f32_e32 v1, v18, v66
	v_mul_f32_e32 v2, v19, v66
	v_cvt_pk_bf16_f32 v1, v1, v2
	global_store_dwordx2 v[68:69], v[0:1], off offset:224
	v_mul_f32_e32 v0, v44, v66
	v_mul_f32_e32 v1, v45, v66
	v_cvt_pk_bf16_f32 v0, v0, v1
	v_mul_f32_e32 v1, v46, v66
	v_mul_f32_e32 v2, v47, v66
	v_cvt_pk_bf16_f32 v1, v1, v2
	global_store_dwordx2 v[68:69], v[0:1], off offset:256
	v_mul_f32_e32 v0, v40, v66
	v_mul_f32_e32 v1, v41, v66
	v_cvt_pk_bf16_f32 v0, v0, v1
	v_mul_f32_e32 v1, v42, v66
	v_mul_f32_e32 v2, v43, v66
	v_cvt_pk_bf16_f32 v1, v1, v2
	global_store_dwordx2 v[68:69], v[0:1], off offset:288
	v_mul_f32_e32 v0, v36, v66
	v_mul_f32_e32 v1, v37, v66
	v_cvt_pk_bf16_f32 v0, v0, v1
	v_mul_f32_e32 v1, v38, v66
	v_mul_f32_e32 v2, v39, v66
	v_cvt_pk_bf16_f32 v1, v1, v2
	global_store_dwordx2 v[68:69], v[0:1], off offset:320
	v_mul_f32_e32 v0, v32, v66
	v_mul_f32_e32 v1, v33, v66
	v_cvt_pk_bf16_f32 v0, v0, v1
	v_mul_f32_e32 v1, v34, v66
	v_mul_f32_e32 v2, v35, v66
	v_cvt_pk_bf16_f32 v1, v1, v2
	global_store_dwordx2 v[68:69], v[0:1], off offset:352
	v_mul_f32_e32 v0, v60, v66
	v_mul_f32_e32 v1, v61, v66
	v_cvt_pk_bf16_f32 v0, v0, v1
	v_mul_f32_e32 v1, v62, v66
	v_mul_f32_e32 v2, v63, v66
	v_cvt_pk_bf16_f32 v1, v1, v2
	global_store_dwordx2 v[68:69], v[0:1], off offset:384
	v_mul_f32_e32 v0, v56, v66
	v_mul_f32_e32 v1, v57, v66
	v_cvt_pk_bf16_f32 v0, v0, v1
	v_mul_f32_e32 v1, v58, v66
	v_mul_f32_e32 v2, v59, v66
	v_cvt_pk_bf16_f32 v1, v1, v2
	global_store_dwordx2 v[68:69], v[0:1], off offset:416
	v_mul_f32_e32 v0, v52, v66
	v_mul_f32_e32 v1, v53, v66
	v_cvt_pk_bf16_f32 v0, v0, v1
	v_mul_f32_e32 v1, v54, v66
	v_mul_f32_e32 v2, v55, v66
	v_cvt_pk_bf16_f32 v1, v1, v2
	global_store_dwordx2 v[68:69], v[0:1], off offset:448
	v_mul_f32_e32 v0, v48, v66
	v_mul_f32_e32 v1, v49, v66
	v_cvt_pk_bf16_f32 v0, v0, v1
	v_mul_f32_e32 v1, v50, v66
	v_mul_f32_e32 v2, v51, v66
	v_cvt_pk_bf16_f32 v1, v1, v2
	global_store_dwordx2 v[68:69], v[0:1], off offset:480
	s_waitcnt lgkmcnt(0)
	s_cbranch_scc1 .LBB0_235
	v_readlane_b32 s16, v253, 49
	s_mov_b64 s[36:37], 0xc000800
